# attention P: lane^32 softmax exchanges via v_permlane32_swap instead of ds_bpermute (18 sites), on top of sort+epi+omov+pk5+vpair
# baseline (speedup 1.0000x reference)
.LBB0_1304:
	s_andn2_b64 vcc, exec, s[76:77]
	v_add_u32_e32 v72, 0x4800, v216
	s_waitcnt lgkmcnt(0)
	v_mov_b32_e32 v4, v36
	s_nop 1
	v_permlane32_swap_b32_e32 v4, v36
	v_max3_f32 v75, v36, v4, s46
	v_add_u32_e32 v4, v197, v149
	v_add_u32_e32 v74, 0x4800, v4
	s_cbranch_vccnz .LBB0_1309
	ds_read_b128 v[4:7], v61
	ds_read_b128 v[36:39], v61 offset:32
	v_cmp_lt_i32_e32 vcc, -1, v64
	s_waitcnt lgkmcnt(1)
	v_mfma_f32_32x32x16_bf16 v[4:19], v[4:7], v[100:103], 0
	s_waitcnt lgkmcnt(0)
	v_mfma_f32_32x32x16_bf16 v[4:19], v[36:39], v[104:107], v[4:19]
	ds_read_b128 v[36:39], v61 offset:64
	s_waitcnt lgkmcnt(0)
	v_mfma_f32_32x32x16_bf16 v[4:19], v[36:39], v[108:111], v[4:19]
	ds_read_b128 v[36:39], v61 offset:96
	s_waitcnt lgkmcnt(0)
	v_mfma_f32_32x32x16_bf16 v[4:19], v[36:39], v[112:115], v[4:19]
	s_nop 11
	v_add_f32_e32 v4, v21, v4
	v_cndmask_b32_e32 v4, v214, v4, vcc
	v_sub_f32_e32 v4, v4, v75
	v_exp_f32_e32 v21, v4
	v_add_f32_e32 v4, v34, v5
	v_cmp_lt_i32_e32 vcc, 0, v64
	v_add_f32_e32 v3, v3, v19
	s_nop 0
	v_cndmask_b32_e32 v4, v214, v4, vcc
	v_sub_f32_e32 v4, v4, v75
	v_exp_f32_e32 v5, v4
	v_add_f32_e32 v4, v23, v6
	v_cmp_lt_i32_e32 vcc, 1, v64
	v_add_f32_e32 v6, v22, v10
	s_nop 0
	v_cndmask_b32_e32 v4, v214, v4, vcc
	v_sub_f32_e32 v4, v4, v75
	v_exp_f32_e32 v23, v4
	v_add_f32_e32 v4, v33, v7
	v_cmp_lt_i32_e32 vcc, 2, v64
	s_nop 1
	v_cndmask_b32_e32 v4, v214, v4, vcc
	v_sub_f32_e32 v4, v4, v75
	v_exp_f32_e32 v7, v4
	v_add_f32_e32 v4, v20, v8
	v_cmp_lt_i32_e32 vcc, 7, v64
	v_add_f32_e32 v8, v30, v12
	s_nop 0
	v_cndmask_b32_e32 v4, v214, v4, vcc
	v_sub_f32_e32 v4, v4, v75
	v_exp_f32_e32 v20, v4
	v_add_f32_e32 v4, v32, v9
	v_cmp_lt_i32_e32 vcc, 8, v64
	s_nop 1
	v_cndmask_b32_e32 v4, v214, v4, vcc
	v_cmp_lt_i32_e32 vcc, 9, v64
	v_sub_f32_e32 v4, v4, v75
	v_exp_f32_e32 v4, v4
	v_cndmask_b32_e32 v6, v214, v6, vcc
	v_sub_f32_e32 v6, v6, v75
	v_exp_f32_e32 v22, v6
	v_add_f32_e32 v6, v31, v11
	v_cmp_lt_i32_e32 vcc, 10, v64
	s_nop 1
	v_cndmask_b32_e32 v6, v214, v6, vcc
	v_cmp_lt_i32_e32 vcc, 15, v64
	v_sub_f32_e32 v6, v6, v75
	v_exp_f32_e32 v6, v6
	v_cndmask_b32_e32 v8, v214, v8, vcc
	v_sub_f32_e32 v8, v8, v75
	v_exp_f32_e32 v39, v8
	v_add_f32_e32 v8, v29, v13
	v_cmp_lt_i32_e32 vcc, 16, v64
	v_add_f32_e32 v12, v20, v4
	v_add_f32_e32 v13, v21, v5
	s_nop 0
	v_cndmask_b32_e32 v8, v214, v8, vcc
	v_sub_f32_e32 v8, v8, v75
	v_exp_f32_e32 v41, v8
	v_add_f32_e32 v8, v28, v14
	v_cmp_lt_i32_e32 vcc, 17, v64
	v_add_f32_e32 v12, v22, v12
	v_add_f32_e32 v13, v23, v13
	v_cvt_pk_bf16_f32 v128, v39, v41
	v_cndmask_b32_e32 v8, v214, v8, vcc
	v_sub_f32_e32 v8, v8, v75
	v_exp_f32_e32 v43, v8
	v_add_f32_e32 v8, v27, v15
	v_cmp_lt_i32_e32 vcc, 18, v64
	v_fma_f32 v12, v6, 0.5, v12
	v_fma_f32 v13, v7, 0.5, v13
	v_cvt_pk_bf16_f32 v27, v22, v6
	v_cndmask_b32_e32 v8, v214, v8, vcc
	v_sub_f32_e32 v8, v8, v75
	v_exp_f32_e32 v37, v8
	v_add_f32_e32 v8, v26, v16
	v_cmp_lt_i32_e32 vcc, 23, v64
	v_cvt_pk_bf16_f32 v26, v20, v4
	v_cvt_pk_bf16_f32 v129, v43, v37
	v_cndmask_b32_e32 v8, v214, v8, vcc
	v_sub_f32_e32 v8, v8, v75
	v_exp_f32_e32 v38, v8
	v_add_f32_e32 v8, v25, v17
	v_cmp_lt_i32_e32 vcc, 24, v64
	v_cvt_pk_bf16_f32 v25, v23, v7
	s_nop 0
	v_cndmask_b32_e32 v8, v214, v8, vcc
	v_sub_f32_e32 v8, v8, v75
	v_exp_f32_e32 v40, v8
	v_add_f32_e32 v8, v24, v18
	v_cmp_lt_i32_e32 vcc, 25, v64
	v_cvt_pk_bf16_f32 v24, v21, v5
	v_add_f32_e32 v10, v38, v40
	v_add_f32_e32 v11, v39, v41
	v_cndmask_b32_e32 v8, v214, v8, vcc
	v_cmp_lt_i32_e32 vcc, 26, v64
	v_sub_f32_e32 v8, v8, v75
	v_exp_f32_e32 v42, v8
	v_cndmask_b32_e32 v3, v214, v3, vcc
	v_sub_f32_e32 v3, v3, v75
	v_exp_f32_e32 v36, v3
	v_add_f32_e32 v3, 0, v21
	v_add_f32_e32 v3, v5, v3
	v_add_f32_e32 v3, v23, v3
	v_mul_f32_e32 v8, 0.5, v36
	v_mul_f32_e32 v9, 0.5, v37
	v_add_f32_e32 v3, v7, v3
	ds_bpermute_b32 v14, v179, v9
	ds_bpermute_b32 v98, v179, v8
	v_mul_f32_e32 v8, 0.5, v6
	v_mul_f32_e32 v9, 0.5, v7
	v_add_f32_e32 v3, v20, v3
	ds_bpermute_b32 v9, v179, v9
	ds_bpermute_b32 v15, v179, v8
	v_add_f32_e32 v3, v4, v3
	v_add_f32_e32 v3, v22, v3
	v_add_f32_e32 v3, v6, v3
	ds_read2_b64 v[4:7], v74 offset1:2
	ds_read2_b64 v[44:47], v74 offset0:4 offset1:6
	ds_read2_b64 v[20:23], v72 offset1:2
	ds_read2_b64 v[48:51], v72 offset0:4 offset1:6
	v_add_f32_e32 v10, v42, v10
	v_add_f32_e32 v11, v43, v11
	s_waitcnt lgkmcnt(4)
	v_cndmask_b32_e64 v8, v15, v9, s[10:11]
	v_cndmask_b32_e64 v9, v9, 0, s[10:11]
	v_fma_f32 v10, v36, 0.5, v10
	v_fma_f32 v11, v37, 0.5, v11
	v_add_f32_e32 v54, v8, v12
	v_add_f32_e32 v55, v9, v13
	v_cndmask_b32_e64 v9, v14, v15, s[10:11]
	v_cndmask_b32_e64 v8, v98, v14, s[10:11]
	v_add_f32_e32 v52, v10, v8
	v_add_f32_e32 v53, v11, v9
	s_waitcnt lgkmcnt(3)
	v_mfma_f32_32x32x16_bf16 v[4:19], v[4:7], v[24:27], 0
	v_cvt_pk_bf16_f32 v130, v38, v40
	v_cvt_pk_bf16_f32 v131, v42, v36
	v_add_f32_e32 v3, v39, v3
	v_add_f32_e32 v3, v41, v3
	v_add_f32_e32 v3, v43, v3
	v_add_f32_e32 v3, v37, v3
	v_add_f32_e32 v3, v38, v3
	s_waitcnt lgkmcnt(1)
	v_mfma_f32_32x32x16_bf16 v[20:35], v[20:23], v[24:27], 0
	v_add_f32_e32 v3, v40, v3
	v_add_f32_e32 v3, v42, v3
	v_add_f32_e32 v3, v36, v3
	v_mfma_f32_32x32x16_bf16 v[4:19], v[44:47], v[128:131], v[4:19]
	s_waitcnt lgkmcnt(0)
	v_mfma_f32_32x32x16_bf16 v[20:35], v[48:51], v[128:131], v[20:35]
	s_andn2_b64 vcc, exec, s[54:55]
	v_mov_b32_e32 v60, 0
	s_cbranch_vccnz .LBB0_1310

.LBB0_1313:
	s_cmp_lt_i32 s48, 16
	s_waitcnt lgkmcnt(0)
	v_mov_b32_e32 v40, v3
	s_nop 1
	v_permlane32_swap_b32_e32 v40, v3
	v_add_f32_e32 v3, v3, v40
	v_max_f32_e32 v3, 0xda24260, v3
	v_div_scale_f32 v40, s[0:1], v3, v3, 1.0
	v_rcp_f32_e32 v41, v40
	v_div_scale_f32 v42, vcc, 1.0, v3, 1.0
	s_mov_b64 s[0:1], -1
	v_fma_f32 v43, -v40, v41, 1.0
	v_fmac_f32_e32 v41, v43, v41
	v_mul_f32_e32 v43, v42, v41
	v_fma_f32 v44, -v40, v43, v42
	v_fmac_f32_e32 v43, v44, v41
	v_fma_f32 v40, -v40, v43, v42
	v_div_fmas_f32 v40, v40, v41, v43
	v_div_fixup_f32 v40, v40, v3, 1.0
	v_mul_f32_e32 v41, v54, v40
	v_mul_f32_e32 v4, v4, v40
	v_mul_f32_e32 v5, v5, v40
	v_mul_f32_e32 v6, v6, v40
	v_mul_f32_e32 v7, v7, v40
	v_mul_f32_e32 v20, v20, v40
	v_mul_f32_e32 v21, v21, v40
	v_mul_f32_e32 v22, v22, v40
	v_mul_f32_e32 v23, v23, v40
	v_mul_f32_e32 v6, v132, v6
	v_mul_f32_e32 v7, v132, v7
	v_mul_f32_e32 v4, v132, v4
	v_mul_f32_e32 v5, v132, v5
	v_mul_f32_e32 v8, v8, v40
	v_mul_f32_e32 v9, v9, v40
	v_mul_f32_e32 v10, v10, v40
	v_mul_f32_e32 v11, v11, v40
	ds_write_b128 v193, v[4:7]
	v_mul_f32_e32 v6, v132, v22
	v_mul_f32_e32 v7, v132, v23
	v_mul_f32_e32 v4, v132, v20
	v_mul_f32_e32 v5, v132, v21
	v_mul_f32_e32 v24, v24, v40
	v_mul_f32_e32 v25, v25, v40
	v_mul_f32_e32 v26, v26, v40
	v_mul_f32_e32 v27, v27, v40
	ds_write_b128 v193, v[4:7] offset:128
	v_mul_f32_e32 v6, v132, v10
	v_mul_f32_e32 v7, v132, v11
	v_mul_f32_e32 v4, v132, v8
	v_mul_f32_e32 v5, v132, v9
	v_mul_f32_e32 v12, v12, v40
	v_mul_f32_e32 v13, v13, v40
	v_mul_f32_e32 v14, v14, v40
	v_mul_f32_e32 v15, v15, v40
	ds_write_b128 v193, v[4:7] offset:32
	v_mul_f32_e32 v6, v132, v26
	v_mul_f32_e32 v7, v132, v27
	v_mul_f32_e32 v4, v132, v24
	v_mul_f32_e32 v5, v132, v25
	v_mul_f32_e32 v28, v28, v40
	v_mul_f32_e32 v29, v29, v40
	v_mul_f32_e32 v30, v30, v40
	v_mul_f32_e32 v31, v31, v40
	ds_write_b128 v193, v[4:7] offset:160
	v_mul_f32_e32 v6, v132, v14
	v_mul_f32_e32 v7, v132, v15
	v_mul_f32_e32 v4, v132, v12
	v_mul_f32_e32 v5, v132, v13
	v_mul_f32_e32 v16, v16, v40
	v_mul_f32_e32 v17, v17, v40
	v_mul_f32_e32 v18, v18, v40
	v_mul_f32_e32 v19, v19, v40
	ds_write_b128 v193, v[4:7] offset:64
	v_mul_f32_e32 v6, v132, v30
	v_mul_f32_e32 v7, v132, v31
	v_mul_f32_e32 v4, v132, v28
	v_mul_f32_e32 v5, v132, v29
	v_mul_f32_e32 v32, v32, v40
	v_mul_f32_e32 v33, v33, v40
	v_mul_f32_e32 v34, v34, v40
	v_mul_f32_e32 v35, v35, v40
	ds_write_b128 v193, v[4:7] offset:192
	v_mul_f32_e32 v6, v132, v18
	v_mul_f32_e32 v7, v132, v19
	v_mul_f32_e32 v4, v132, v16
	v_mul_f32_e32 v5, v132, v17
	ds_write_b128 v193, v[4:7] offset:96
	v_mul_f32_e32 v6, v132, v34
	v_mul_f32_e32 v7, v132, v35
	v_mul_f32_e32 v4, v132, v32
	v_mul_f32_e32 v5, v132, v33
	v_mul_f32_e32 v3, v55, v40
	ds_write_b128 v193, v[4:7] offset:224
	v_add_u32_e32 v4, 0x8c00, v198
	v_mul_f32_e32 v42, v53, v40
	v_mul_f32_e32 v43, v52, v40
	v_mul_f32_e32 v44, v59, v40
	v_mul_f32_e32 v45, v58, v40
	v_mul_f32_e32 v46, v57, v40
	v_mul_f32_e32 v47, v56, v40
	v_mul_f32_e32 v48, v63, v40
	v_mul_f32_e32 v49, v62, v40
	v_mul_f32_e32 v50, v61, v40
	v_mul_f32_e32 v51, v60, v40
	v_mul_f32_e32 v39, v39, v40
	v_mul_f32_e32 v38, v38, v40
	v_mul_f32_e32 v37, v37, v40
	v_mul_f32_e32 v36, v36, v40
	ds_write2_b32 v4, v3, v41 offset1:2
	ds_write2_b32 v4, v42, v43 offset0:4 offset1:6
	ds_write2_b32 v4, v44, v45 offset0:8 offset1:10
	ds_write2_b32 v4, v46, v47 offset0:12 offset1:14
	ds_write2_b32 v4, v48, v49 offset0:16 offset1:18
	ds_write2_b32 v4, v50, v51 offset0:20 offset1:22
	ds_write2_b32 v4, v39, v38 offset0:24 offset1:26
	ds_write2_b32 v4, v37, v36 offset0:28 offset1:30
	s_waitcnt lgkmcnt(0)
	s_barrier
	s_cbranch_scc0 .LBB0_1315
	s_lshl_b32 s0, 2, s48
	s_add_i32 s44, s0, -1
	s_mov_b64 s[0:1], 0

.LBB0_1416:
	v_lshrrev_b32_e32 v3, s42, v159
	v_and_b32_e32 v3, 1, v3
	v_cmp_eq_u32_e64 s[2:3], 1, v3
	s_or_b64 s[8:9], s[28:29], s[2:3]
	v_cndmask_b32_e64 v3, 0, 1, s[8:9]
	v_cmp_ne_u32_e32 vcc, 0, v3
	s_cbranch_vccz .LBB0_1443
	s_cmp_lt_i32 s42, s48
	s_cselect_b64 s[24:25], -1, 0
	s_cmp_ge_i32 s42, s48
	s_cselect_b64 s[30:31], -1, 0
	s_mov_b64 s[26:27], -1
	s_and_b64 vcc, exec, s[20:21]
	v_lshl_or_b32 v165, s42, 6, v136
	s_cbranch_vccz .LBB0_1426
	v_sub_u32_e32 v68, v161, v165
	v_cvt_f32_i32_e32 v221, v68
	v_add_u32_e32 v219, s38, v176
	s_and_b64 vcc, exec, s[30:31]
	v_add_u32_e32 v69, v219, v177
	v_add_u32_e32 v220, v219, v178
	s_cbranch_vccz .LBB0_1422
	v_mov_b32_e32 v3, v157
	ds_read_b128 v[52:55], v69
	ds_read_b128 v[56:59], v69 offset:32
	v_mul_f32_e64 v36, v221, -v3
	v_cndmask_b32_e64 v66, v214, v36, s[2:3]
	v_mov_b32_e32 v74, v3
	v_fma_f32 v38, 0, v3, v66
	v_fmamk_f32 v42, v3, 0x41000000, v66
	v_fmamk_f32 v46, v3, 0x41800000, v66
	v_fmamk_f32 v50, v3, 0x41c00000, v66
	v_add_f32_e32 v36, v2, v38
	v_add_f32_e32 v37, v3, v38
	v_fma_f32 v39, v74, s65, v38
	v_fma_f32 v38, v74, s64, v38
	v_add_f32_e32 v40, v2, v42
	v_add_f32_e32 v41, v3, v42
	v_fma_f32 v43, v74, s65, v42
	v_fma_f32 v42, v74, s64, v42
	v_add_f32_e32 v44, v2, v46
	v_add_f32_e32 v45, v3, v46
	v_fma_f32 v47, v74, s65, v46
	v_fma_f32 v46, v74, s64, v46
	v_add_f32_e32 v48, v2, v50
	v_add_f32_e32 v49, v3, v50
	v_fma_f32 v51, v74, s65, v50
	v_fma_f32 v50, v74, s64, v50
	v_fmamk_f32 v62, v3, 0x42200000, v66
	v_fmamk_f32 v64, v3, 0x42400000, v66
	s_waitcnt lgkmcnt(1)
	v_mfma_f32_32x32x16_bf16 v[36:51], v[52:55], v[100:103], v[36:51]
	v_cmp_lt_i32_e32 vcc, -1, v68
	s_waitcnt lgkmcnt(0)
	v_mfma_f32_32x32x16_bf16 v[36:51], v[56:59], v[104:107], v[36:51]
	ds_read_b128 v[52:55], v69 offset:64
	ds_read_b128 v[58:61], v69 offset:96
	ds_read_b128 v[70:73], v220
	v_add_f32_e64 v56, v2, v62
	v_add_f32_e64 v57, v3, v62
	s_waitcnt lgkmcnt(2)
	v_mfma_f32_32x32x16_bf16 v[36:51], v[52:55], v[108:111], v[36:51]
	v_fmamk_f32 v54, v3, 0x42000000, v66
	v_fmac_f32_e32 v66, 0x42600000, v3
	v_add_f32_e64 v52, v2, v54
	v_add_f32_e64 v53, v3, v54
	v_fma_f32 v55, v74, s65, v54
	v_fma_f32 v54, v74, s64, v54
	s_waitcnt lgkmcnt(1)
	v_mfma_f32_32x32x16_bf16 v[36:51], v[58:61], v[112:115], v[36:51]
	v_fma_f32 v58, v74, s64, v62
	v_fma_f32 v59, v74, s65, v62
	v_add_f32_e64 v60, v2, v64
	v_add_f32_e64 v61, v3, v64
	v_fma_f32 v62, v74, s64, v64
	v_fma_f32 v63, v74, s65, v64
	v_add_f32_e32 v64, v2, v66
	v_add_f32_e32 v65, v3, v66
	v_fma_f32 v67, v74, s65, v66
	v_fma_f32 v66, v74, s64, v66
	ds_read_b128 v[74:77], v220 offset:32
	s_nop 2
	v_cndmask_b32_e32 v86, v214, v36, vcc
	s_waitcnt lgkmcnt(1)
	v_mfma_f32_32x32x16_bf16 v[52:67], v[70:73], v[100:103], v[52:67]
	ds_read_b128 v[70:73], v220 offset:64
	ds_read_b128 v[78:81], v220 offset:96
	v_cmp_lt_i32_e32 vcc, 0, v68
	s_nop 1
	v_cndmask_b32_e32 v87, v214, v37, vcc
	v_cmp_lt_i32_e32 vcc, 1, v68
	v_max3_f32 v3, v86, s97, v87
	s_waitcnt lgkmcnt(2)
	v_mfma_f32_32x32x16_bf16 v[52:67], v[74:77], v[104:107], v[52:67]
	v_cndmask_b32_e32 v94, v214, v38, vcc
	v_cmp_lt_i32_e32 vcc, 2, v68
	s_nop 1
	v_cndmask_b32_e32 v95, v214, v39, vcc
	v_cmp_lt_i32_e32 vcc, 7, v68
	v_max3_f32 v3, v3, v94, v95
	s_waitcnt lgkmcnt(1)
	v_mfma_f32_32x32x16_bf16 v[52:67], v[70:73], v[108:111], v[52:67]
	v_cndmask_b32_e32 v98, v214, v40, vcc
	v_cmp_lt_i32_e32 vcc, 8, v68
	s_nop 1
	v_cndmask_b32_e32 v99, v214, v41, vcc
	v_cmp_lt_i32_e32 vcc, 9, v68
	v_max3_f32 v3, v3, v98, v99
	s_waitcnt lgkmcnt(0)
	v_mfma_f32_32x32x16_bf16 v[52:67], v[78:81], v[112:115], v[52:67]
	v_cndmask_b32_e32 v96, v214, v42, vcc
	v_cmp_lt_i32_e32 vcc, 10, v68
	s_nop 1
	v_cndmask_b32_e32 v97, v214, v43, vcc
	v_cmp_lt_i32_e32 vcc, 15, v68
	v_max3_f32 v3, v3, v96, v97
	s_nop 0
	v_cndmask_b32_e32 v170, v214, v44, vcc
	v_cmp_lt_i32_e32 vcc, 16, v68
	s_nop 1
	v_cndmask_b32_e32 v171, v214, v45, vcc
	v_cmp_lt_i32_e32 vcc, 17, v68
	v_max3_f32 v3, v3, v170, v171
	s_nop 0
	v_cndmask_b32_e32 v90, v214, v46, vcc
	v_cmp_lt_i32_e32 vcc, 18, v68
	s_nop 1
	v_cndmask_b32_e32 v91, v214, v47, vcc
	v_cmp_lt_i32_e32 vcc, 23, v68
	v_max3_f32 v3, v3, v90, v91
	s_nop 0
	v_cndmask_b32_e32 v92, v214, v48, vcc
	v_cmp_lt_i32_e32 vcc, 24, v68
	s_nop 1
	v_cndmask_b32_e32 v93, v214, v49, vcc
	v_cmp_lt_i32_e32 vcc, 25, v68
	v_max3_f32 v3, v3, v92, v93
	s_nop 0
	v_cndmask_b32_e32 v88, v214, v50, vcc
	v_cmp_lt_i32_e32 vcc, 26, v68
	s_nop 1
	v_cndmask_b32_e32 v89, v214, v51, vcc
	v_cmp_lt_i32_e32 vcc, 31, v68
	v_max3_f32 v3, v3, v88, v89
	s_nop 0
	v_cndmask_b32_e32 v84, v214, v52, vcc
	v_cmp_lt_i32_e32 vcc, 32, v68
	s_nop 1
	v_cndmask_b32_e32 v85, v214, v53, vcc
	v_cmp_lt_i32_e32 vcc, 33, v68
	v_max3_f32 v3, v3, v84, v85
	s_nop 0
	v_cndmask_b32_e32 v82, v214, v54, vcc
	v_cmp_lt_i32_e32 vcc, 34, v68
	s_nop 1
	v_cndmask_b32_e32 v83, v214, v55, vcc
	v_cmp_lt_i32_e32 vcc, 39, v68
	v_max3_f32 v3, v3, v82, v83
	s_nop 0
	v_cndmask_b32_e32 v80, v214, v56, vcc
	v_cmp_lt_i32_e32 vcc, 40, v68
	s_nop 1
	v_cndmask_b32_e32 v81, v214, v57, vcc
	v_cmp_lt_i32_e32 vcc, 41, v68
	v_max3_f32 v3, v3, v80, v81
	s_nop 0
	v_cndmask_b32_e32 v78, v214, v58, vcc
	v_cmp_lt_i32_e32 vcc, 42, v68
	s_nop 1
	v_cndmask_b32_e32 v79, v214, v59, vcc
	v_cmp_lt_i32_e32 vcc, 47, v68
	v_max3_f32 v3, v3, v78, v79
	s_nop 0
	v_cndmask_b32_e32 v76, v214, v60, vcc
	v_cmp_lt_i32_e32 vcc, 48, v68
	s_nop 1
	v_cndmask_b32_e32 v77, v214, v61, vcc
	v_cmp_lt_i32_e32 vcc, 49, v68
	v_max3_f32 v3, v3, v76, v77
	s_nop 0
	v_cndmask_b32_e32 v74, v214, v62, vcc
	v_cmp_lt_i32_e32 vcc, 50, v68
	s_nop 1
	v_cndmask_b32_e32 v75, v214, v63, vcc
	v_cmp_lt_i32_e32 vcc, 55, v68
	v_max3_f32 v3, v3, v74, v75
	s_nop 0
	v_cndmask_b32_e32 v70, v214, v64, vcc
	v_cmp_lt_i32_e32 vcc, 56, v68
	s_nop 1
	v_cndmask_b32_e32 v71, v214, v65, vcc
	v_cmp_lt_i32_e32 vcc, 57, v68
	v_max3_f32 v3, v3, v70, v71
	s_nop 0
	v_cndmask_b32_e32 v72, v214, v66, vcc
	v_cmp_lt_i32_e32 vcc, 58, v68
	s_nop 1
	v_cndmask_b32_e32 v73, v214, v67, vcc
	v_max3_f32 v3, v3, v72, v73
	s_nop 3
	s_waitcnt lgkmcnt(0)
	v_mov_b32_e32 v36, v3
	s_nop 1
	v_permlane32_swap_b32_e32 v36, v3
	v_max_f32_e32 v36, v36, v36
	v_max_f32_e32 v3, v3, v36
	v_max3_f32 v132, v218, v3, s46
	v_sub_f32_e32 v3, v218, v132
	v_exp_f32_e32 v68, v3
	s_nop 2
	v_cmp_eq_f32_e32 vcc, 1.0, v68
	s_cmp_eq_u64 vcc, exec
	s_nop 8
	s_cbranch_scc1 .LBB0_1421
	v_mul_f32_e32 v34, v34, v68
	v_mul_f32_e32 v35, v35, v68
	v_mul_f32_e32 v32, v32, v68
	v_mul_f32_e32 v33, v33, v68
	v_mul_f32_e32 v30, v30, v68
	v_mul_f32_e32 v31, v31, v68
	v_mul_f32_e32 v28, v28, v68
	v_mul_f32_e32 v29, v29, v68
	v_mul_f32_e32 v26, v26, v68
	v_mul_f32_e32 v27, v27, v68
	v_mul_f32_e32 v24, v24, v68
	v_mul_f32_e32 v25, v25, v68
	v_mul_f32_e32 v22, v22, v68
	v_mul_f32_e32 v23, v23, v68
	v_mul_f32_e32 v20, v20, v68
	v_mul_f32_e32 v21, v21, v68
	v_mul_f32_e32 v18, v18, v68
	v_mul_f32_e32 v19, v19, v68
	v_mul_f32_e32 v16, v16, v68
	v_mul_f32_e32 v17, v17, v68
	v_mul_f32_e32 v14, v14, v68
	v_mul_f32_e32 v15, v15, v68
	v_mul_f32_e32 v12, v12, v68
	v_mul_f32_e32 v13, v13, v68
	v_mul_f32_e32 v10, v10, v68
	v_mul_f32_e32 v11, v11, v68
	v_mul_f32_e32 v8, v8, v68
	v_mul_f32_e32 v9, v9, v68
	v_mul_f32_e32 v6, v6, v68
	v_mul_f32_e32 v7, v7, v68
	v_mul_f32_e32 v4, v4, v68
	v_mul_f32_e32 v5, v5, v68
.LBB0_1421:
	v_sub_f32_e32 v94, v94, v132
	v_sub_f32_e32 v95, v95, v132
	v_lshl_add_u32 v3, v136, 1, s38
	v_exp_f32_e32 v230, v94
	v_exp_f32_e32 v231, v95
	v_sub_f32_e32 v94, v98, v132
	v_sub_f32_e32 v95, v99, v132
	v_sub_f32_e32 v86, v86, v132
	v_sub_f32_e32 v87, v87, v132
	v_exp_f32_e32 v98, v94
	v_exp_f32_e32 v99, v95
	v_sub_f32_e32 v94, v96, v132
	v_sub_f32_e32 v95, v97, v132
	v_exp_f32_e32 v86, v86
	v_exp_f32_e32 v232, v94
	v_add_u32_e32 v94, v3, v190
	v_add_u32_e32 v186, 0x2000, v94
	v_exp_f32_e32 v233, v95
	ds_read2_b64 v[94:97], v186 offset0:128 offset1:130
	v_add_u32_e32 v3, v3, v191
	v_add_u32_e32 v3, 0x2000, v3
	ds_read2_b64 v[226:229], v3 offset0:128 offset1:130
	v_exp_f32_e32 v87, v87
	v_sub_f32_e32 v90, v90, v132
	v_sub_f32_e32 v91, v91, v132
	v_cvt_pk_bf16_f32 v223, v230, v231
	v_exp_f32_e32 v234, v90
	v_exp_f32_e32 v235, v91
	v_sub_f32_e32 v90, v92, v132
	v_sub_f32_e32 v91, v93, v132
	v_cvt_pk_bf16_f32 v222, v86, v87
	v_cvt_pk_bf16_f32 v224, v98, v99
	v_cvt_pk_bf16_f32 v225, v232, v233
	v_exp_f32_e32 v236, v90
	v_exp_f32_e32 v237, v91
	ds_read2_b64 v[90:93], v186 offset0:132 offset1:134
	s_waitcnt lgkmcnt(2)
	v_mfma_f32_32x32x16_bf16 v[20:35], v[94:97], v[222:225], v[20:35]
	v_add_f32_e64 v170, v170, -v132
	v_add_f32_e64 v171, v171, -v132
	v_add_f32_e64 v88, v88, -v132
	v_add_f32_e64 v89, v89, -v132
	v_exp_f32_e32 v170, v170
	v_exp_f32_e32 v171, v171
	v_cvt_pk_bf16_f32 v95, v234, v235
	v_cvt_pk_bf16_f32 v96, v236, v237
	v_cvt_pk_bf16_f32 v94, v170, v171
	s_waitcnt lgkmcnt(1)
	v_mfma_f32_32x32x16_bf16 v[4:19], v[226:229], v[222:225], v[4:19]
	v_exp_f32_e32 v222, v88
	v_exp_f32_e32 v223, v89
	s_nop 0
	v_cvt_pk_bf16_f32 v97, v222, v223
	s_waitcnt lgkmcnt(0)
	s_nop 0
	v_mfma_f32_32x32x16_bf16 v[20:35], v[90:93], v[94:97], v[20:35]
	ds_read2_b64 v[88:91], v3 offset0:132 offset1:134
	s_waitcnt lgkmcnt(0)
	v_mfma_f32_32x32x16_bf16 v[4:19], v[88:91], v[94:97], v[4:19]
	v_add_f32_e64 v80, v80, -v132
	v_add_f32_e64 v81, v81, -v132
	v_add_f32_e64 v78, v78, -v132
	v_add_f32_e64 v79, v79, -v132
	v_exp_f32_e32 v94, v80
	v_exp_f32_e32 v95, v81
	v_exp_f32_e32 v96, v78
	v_exp_f32_e32 v97, v79
	v_sub_f32_e32 v80, v76, v132
	v_sub_f32_e32 v81, v77, v132
	ds_read2_b64 v[76:79], v186 offset0:136 offset1:138
	v_sub_f32_e32 v84, v84, v132
	v_sub_f32_e32 v85, v85, v132
	v_sub_f32_e32 v82, v82, v132
	v_sub_f32_e32 v83, v83, v132
	ds_read2_b64 v[88:91], v3 offset0:136 offset1:138
	v_exp_f32_e32 v84, v84
	v_exp_f32_e32 v85, v85
	v_exp_f32_e32 v92, v82
	v_exp_f32_e32 v93, v83
	v_sub_f32_e32 v74, v74, v132
	v_sub_f32_e32 v75, v75, v132
	v_sub_f32_e32 v70, v70, v132
	v_sub_f32_e32 v71, v71, v132
	v_exp_f32_e32 v224, v80
	v_exp_f32_e32 v225, v81
	v_cvt_pk_bf16_f32 v80, v84, v85
	v_cvt_pk_bf16_f32 v81, v92, v93
	v_cvt_pk_bf16_f32 v82, v94, v95
	v_cvt_pk_bf16_f32 v83, v96, v97
	v_exp_f32_e32 v226, v74
	v_exp_f32_e32 v227, v75
	v_exp_f32_e32 v228, v70
	v_exp_f32_e32 v229, v71
	v_sub_f32_e32 v74, v72, v132
	v_sub_f32_e32 v75, v73, v132
	ds_read2_b64 v[70:73], v186 offset0:140 offset1:142
	s_waitcnt lgkmcnt(2)
	v_mfma_f32_32x32x16_bf16 v[20:35], v[76:79], v[80:83], v[20:35]
	v_cvt_pk_bf16_f32 v78, v224, v225
	v_cvt_pk_bf16_f32 v79, v226, v227
	s_mov_b64 s[26:27], 0
	s_waitcnt lgkmcnt(1)
	v_mfma_f32_32x32x16_bf16 v[4:19], v[88:91], v[80:83], v[4:19]
	v_exp_f32_e32 v82, v74
	v_exp_f32_e32 v83, v75
	v_cvt_pk_bf16_f32 v80, v228, v229
	ds_read2_b64 v[74:77], v3 offset0:140 offset1:142
	v_cvt_pk_bf16_f32 v81, v82, v83
	s_waitcnt lgkmcnt(1)
	s_nop 0
	v_mfma_f32_32x32x16_bf16 v[20:35], v[70:73], v[78:81], v[20:35]
	v_add_f32_e64 v70, v86, 0
	v_add_f32_e64 v71, v87, 0
	v_add_f32_e64 v70, v230, v70
	v_add_f32_e64 v71, v231, v71
	v_add_f32_e64 v70, v98, v70
	v_add_f32_e64 v71, v99, v71
	v_add_f32_e32 v70, v232, v70
	v_add_f32_e32 v71, v233, v71
	s_waitcnt lgkmcnt(0)
	v_mfma_f32_32x32x16_bf16 v[4:19], v[74:77], v[78:81], v[4:19]
	v_add_f32_e64 v70, v170, v70
	v_add_f32_e64 v71, v171, v71
	v_add_f32_e64 v70, v234, v70
	v_add_f32_e64 v71, v235, v71
	v_add_f32_e64 v70, v236, v70
	v_add_f32_e64 v71, v237, v71
	v_add_f32_e32 v70, v222, v70
	v_add_f32_e32 v71, v223, v71
	s_nop 0
	v_add_f32_e32 v70, v84, v70
	v_add_f32_e32 v71, v85, v71
	s_nop 0
	v_add_f32_e32 v70, v92, v70
	v_add_f32_e32 v71, v93, v71
	s_nop 0
	v_add_f32_e32 v70, v94, v70
	v_add_f32_e32 v71, v95, v71
	s_nop 0
	v_add_f32_e32 v70, v96, v70
	v_add_f32_e32 v71, v97, v71
	s_nop 0
	v_add_f32_e32 v70, v224, v70
	v_add_f32_e32 v71, v225, v71
	s_nop 0
	v_add_f32_e32 v70, v226, v70
	v_add_f32_e32 v71, v227, v71
	s_nop 0
	v_add_f32_e32 v70, v228, v70
	v_add_f32_e32 v71, v229, v71
	s_nop 0
	v_add_f32_e32 v70, v82, v70
	v_add_f32_e32 v71, v83, v71
	s_nop 0
	v_add_f32_e32 v3, v70, v71
	s_waitcnt lgkmcnt(0)
	v_mov_b32_e32 v70, v3
	s_nop 1
	v_permlane32_swap_b32_e32 v70, v3
	v_add_f32_e32 v3, v3, v70
	v_fmac_f32_e32 v3, v217, v68
.LBB0_1422:
	s_and_b64 vcc, exec, s[26:27]
	s_cbranch_vccz .LBB0_1441
	v_mov_b32_e32 v3, v157
	s_nop 0
	v_mul_f32_e64 v36, v221, -v3
	v_cndmask_b32_e64 v44, v214, v36, s[2:3]
	v_mov_b32_e32 v46, v3
	v_fma_f32 v36, 0, v3, v44
	v_add_f32_e32 v84, v2, v36
	v_add_f32_e32 v85, v3, v36
	v_fma_f32 v86, v46, s64, v36
	v_fma_f32 v87, v46, s65, v36
	ds_read_b128 v[36:39], v69
	v_fmamk_f32 v40, v3, 0x41000000, v44
	v_add_f32_e32 v88, v2, v40
	v_add_f32_e32 v89, v3, v40
	v_fma_f32 v90, v46, s64, v40
	v_fma_f32 v91, v46, s65, v40
	v_fmamk_f32 v40, v3, 0x41800000, v44
	v_add_f32_e32 v92, v2, v40
	v_add_f32_e32 v93, v3, v40
	v_fma_f32 v94, v46, s64, v40
	v_fma_f32 v95, v46, s65, v40
	v_fmamk_f32 v40, v3, 0x41c00000, v44
	v_add_f32_e32 v96, v2, v40
	v_add_f32_e32 v97, v3, v40
	v_fma_f32 v98, v46, s64, v40
	v_fma_f32 v99, v46, s65, v40
	ds_read_b128 v[40:43], v69 offset:32
	v_fmamk_f32 v48, v3, 0x42000000, v44
	s_waitcnt lgkmcnt(1)
	v_mfma_f32_32x32x16_bf16 v[84:99], v[36:39], v[100:103], v[84:99]
	v_fmamk_f32 v50, v3, 0x42200000, v44
	v_fmamk_f32 v52, v3, 0x42400000, v44
	v_fmac_f32_e32 v44, 0x42600000, v3
	v_fma_f32 v70, v46, s64, v48
	v_fma_f32 v71, v46, s65, v48
	v_add_f32_e32 v72, v2, v50
	v_add_f32_e32 v73, v3, v50
	v_fma_f32 v74, v46, s64, v50
	v_fma_f32 v75, v46, s65, v50
	v_add_f32_e32 v76, v2, v52
	v_add_f32_e32 v77, v3, v52
	s_waitcnt lgkmcnt(0)
	v_mfma_f32_32x32x16_bf16 v[84:99], v[40:43], v[104:107], v[84:99]
	ds_read_b128 v[36:39], v69 offset:64
	ds_read_b128 v[40:43], v69 offset:96
	v_add_f32_e64 v68, v2, v48
	v_add_f32_e64 v69, v3, v48
	v_fma_f32 v78, v46, s64, v52
	v_fma_f32 v79, v46, s65, v52
	v_add_f32_e32 v80, v2, v44
	v_add_f32_e32 v81, v3, v44
	v_fma_f32 v82, v46, s64, v44
	v_fma_f32 v83, v46, s65, v44
	s_nop 1
	s_waitcnt lgkmcnt(1)
	v_mfma_f32_32x32x16_bf16 v[84:99], v[36:39], v[108:111], v[84:99]
	ds_read_b128 v[36:39], v220
	s_nop 5
	s_waitcnt lgkmcnt(1)
	v_mfma_f32_32x32x16_bf16 v[84:99], v[40:43], v[112:115], v[84:99]
	ds_read_b128 v[40:43], v220 offset:32
	s_waitcnt lgkmcnt(1)
	v_mfma_f32_32x32x16_bf16 v[68:83], v[36:39], v[100:103], v[68:83]
	s_nop 8
	v_max3_f32 v3, v84, s97, v85
	v_max3_f32 v3, v3, v86, v87
	v_max3_f32 v3, v3, v88, v89
	v_max3_f32 v3, v3, v90, v91
	v_max3_f32 v3, v3, v92, v93
	v_max3_f32 v3, v3, v94, v95
	v_max3_f32 v3, v3, v96, v97
	s_waitcnt lgkmcnt(0)
	v_mfma_f32_32x32x16_bf16 v[68:83], v[40:43], v[104:107], v[68:83]
	ds_read_b128 v[36:39], v220 offset:64
	ds_read_b128 v[40:43], v220 offset:96
	v_max3_f32 v3, v3, v98, v99
	s_waitcnt lgkmcnt(1)
	v_mfma_f32_32x32x16_bf16 v[68:83], v[36:39], v[108:111], v[68:83]
	s_waitcnt lgkmcnt(0)
	v_mfma_f32_32x32x16_bf16 v[68:83], v[40:43], v[112:115], v[68:83]
	s_nop 11
	v_max3_f32 v3, v3, v68, v69
	v_max3_f32 v3, v3, v70, v71
	v_max3_f32 v3, v3, v72, v73
	v_max3_f32 v3, v3, v74, v75
	v_max3_f32 v3, v3, v76, v77
	v_max3_f32 v3, v3, v78, v79
	v_max3_f32 v3, v3, v80, v81
	v_max3_f32 v3, v3, v82, v83
	s_waitcnt lgkmcnt(0)
	v_mov_b32_e32 v36, v3
	s_nop 1
	v_permlane32_swap_b32_e32 v36, v3
	v_max_f32_e32 v36, v36, v36
	v_max_f32_e32 v3, v3, v36
	v_max3_f32 v132, v218, v3, s46
	v_sub_f32_e32 v3, v218, v132
	v_exp_f32_e32 v170, v3
	s_nop 2
	v_cmp_eq_f32_e32 vcc, 1.0, v170
	s_cmp_eq_u64 vcc, exec
	s_nop 4
	s_cbranch_scc1 .LBB0_1425
	v_mul_f32_e32 v34, v34, v170
	v_mul_f32_e32 v35, v35, v170
	v_mul_f32_e32 v32, v32, v170
	v_mul_f32_e32 v33, v33, v170
	v_mul_f32_e32 v30, v30, v170
	v_mul_f32_e32 v31, v31, v170
	v_mul_f32_e32 v28, v28, v170
	v_mul_f32_e32 v29, v29, v170
	v_mul_f32_e32 v26, v26, v170
	v_mul_f32_e32 v27, v27, v170
	v_mul_f32_e32 v24, v24, v170
	v_mul_f32_e32 v25, v25, v170
	v_mul_f32_e32 v22, v22, v170
	v_mul_f32_e32 v23, v23, v170
	v_mul_f32_e32 v20, v20, v170
	v_mul_f32_e32 v21, v21, v170
	v_mul_f32_e32 v18, v18, v170
	v_mul_f32_e32 v19, v19, v170
	v_mul_f32_e32 v16, v16, v170
	v_mul_f32_e32 v17, v17, v170
	v_mul_f32_e32 v14, v14, v170
	v_mul_f32_e32 v15, v15, v170
	v_mul_f32_e32 v12, v12, v170
	v_mul_f32_e32 v13, v13, v170
	v_mul_f32_e32 v10, v10, v170
	v_mul_f32_e32 v11, v11, v170
	v_mul_f32_e32 v8, v8, v170
	v_mul_f32_e32 v9, v9, v170
	v_mul_f32_e32 v6, v6, v170
	v_mul_f32_e32 v7, v7, v170
	v_mul_f32_e32 v4, v4, v170
	v_mul_f32_e32 v5, v5, v170
.LBB0_1425:
	v_add_u32_e32 v3, v219, v196
	v_sub_f32_e32 v84, v84, v132
	v_sub_f32_e32 v85, v85, v132
	v_sub_f32_e32 v86, v86, v132
	v_sub_f32_e32 v87, v87, v132
	v_sub_f32_e32 v88, v88, v132
	v_sub_f32_e32 v89, v89, v132
	v_sub_f32_e32 v90, v90, v132
	v_sub_f32_e32 v91, v91, v132
	v_add_u32_e32 v171, v3, v190
	v_exp_f32_e32 v84, v84
	v_exp_f32_e32 v85, v85
	v_exp_f32_e32 v86, v86
	v_exp_f32_e32 v87, v87
	v_exp_f32_e32 v88, v88
	v_exp_f32_e32 v89, v89
	v_exp_f32_e32 v90, v90
	v_exp_f32_e32 v91, v91
	v_add_u32_e32 v171, 0x2000, v171
	ds_read2_b64 v[224:227], v171 offset0:128 offset1:130
	ds_read2_b64 v[228:231], v171 offset0:132 offset1:134
	v_add_u32_e32 v3, v3, v191
	v_cvt_pk_bf16_f32 v220, v84, v85
	v_cvt_pk_bf16_f32 v221, v86, v87
	v_cvt_pk_bf16_f32 v222, v88, v89
	v_cvt_pk_bf16_f32 v223, v90, v91
	v_add_u32_e32 v3, 0x2000, v3
	v_sub_f32_e32 v92, v92, v132
	v_sub_f32_e32 v93, v93, v132
	s_waitcnt lgkmcnt(1)
	v_mfma_f32_32x32x16_bf16 v[20:35], v[224:227], v[220:223], v[20:35]
	ds_read2_b64 v[224:227], v3 offset0:128 offset1:130
	ds_read2_b64 v[232:235], v3 offset0:132 offset1:134
	v_add_f32_e64 v94, v94, -v132
	v_add_f32_e64 v95, v95, -v132
	v_add_f32_e64 v96, v96, -v132
	v_add_f32_e64 v97, v97, -v132
	v_sub_f32_e32 v98, v98, v132
	v_sub_f32_e32 v99, v99, v132
	v_exp_f32_e32 v92, v92
	v_exp_f32_e32 v93, v93
	v_exp_f32_e32 v94, v94
	s_waitcnt lgkmcnt(1)
	v_mfma_f32_32x32x16_bf16 v[4:19], v[224:227], v[220:223], v[4:19]
	v_exp_f32_e32 v95, v95
	v_exp_f32_e32 v96, v96
	v_exp_f32_e32 v97, v97
	v_exp_f32_e32 v98, v98
	v_exp_f32_e32 v99, v99
	v_cvt_pk_bf16_f32 v220, v92, v93
	v_cvt_pk_bf16_f32 v221, v94, v95
	v_cvt_pk_bf16_f32 v222, v96, v97
	v_cvt_pk_bf16_f32 v223, v98, v99
	s_nop 1
	v_mfma_f32_32x32x16_bf16 v[20:35], v[228:231], v[220:223], v[20:35]
	s_waitcnt lgkmcnt(0)
	v_mfma_f32_32x32x16_bf16 v[4:19], v[232:235], v[220:223], v[4:19]
	v_add_f32_e64 v74, v74, -v132
	v_add_f32_e64 v75, v75, -v132
	v_add_f32_e64 v68, v68, -v132
	v_add_f32_e64 v69, v69, -v132
	v_add_f32_e64 v70, v70, -v132
	v_add_f32_e64 v71, v71, -v132
	v_sub_f32_e32 v72, v72, v132
	v_sub_f32_e32 v73, v73, v132
	v_exp_f32_e32 v228, v74
	v_exp_f32_e32 v229, v75
	v_sub_f32_e32 v74, v76, v132
	v_sub_f32_e32 v75, v77, v132
	v_exp_f32_e32 v68, v68
	v_exp_f32_e32 v69, v69
	v_exp_f32_e32 v70, v70
	v_exp_f32_e32 v71, v71
	v_exp_f32_e32 v72, v72
	v_exp_f32_e32 v73, v73
	v_exp_f32_e32 v230, v74
	v_exp_f32_e32 v231, v75
	v_sub_f32_e32 v74, v78, v132
	v_sub_f32_e32 v75, v79, v132
	v_cvt_pk_bf16_f32 v76, v72, v73
	v_exp_f32_e32 v232, v74
	v_exp_f32_e32 v233, v75
	v_sub_f32_e32 v74, v80, v132
	v_sub_f32_e32 v75, v81, v132
	ds_read2_b64 v[78:81], v171 offset0:136 offset1:138
	ds_read2_b64 v[220:223], v171 offset0:140 offset1:142
	v_exp_f32_e32 v234, v74
	v_exp_f32_e32 v235, v75
	v_sub_f32_e32 v74, v82, v132
	v_sub_f32_e32 v75, v83, v132
	v_cvt_pk_bf16_f32 v77, v228, v229
	v_exp_f32_e32 v82, v74
	v_exp_f32_e32 v83, v75
	v_cvt_pk_bf16_f32 v74, v68, v69
	v_cvt_pk_bf16_f32 v75, v70, v71
	s_mov_b64 s[26:27], 0
	s_waitcnt lgkmcnt(1)
	v_mfma_f32_32x32x16_bf16 v[20:35], v[78:81], v[74:77], v[20:35]
	ds_read2_b64 v[78:81], v3 offset0:136 offset1:138
	ds_read2_b64 v[224:227], v3 offset0:140 offset1:142
	s_waitcnt lgkmcnt(1)
	v_mfma_f32_32x32x16_bf16 v[4:19], v[78:81], v[74:77], v[4:19]
	v_cvt_pk_bf16_f32 v74, v230, v231
	v_cvt_pk_bf16_f32 v75, v232, v233
	v_cvt_pk_bf16_f32 v76, v234, v235
	v_cvt_pk_bf16_f32 v77, v82, v83
	s_nop 1
	v_mfma_f32_32x32x16_bf16 v[20:35], v[220:223], v[74:77], v[20:35]
	s_waitcnt lgkmcnt(0)
	v_mfma_f32_32x32x16_bf16 v[4:19], v[224:227], v[74:77], v[4:19]
	v_add_f32_e64 v74, v84, 0
	v_add_f32_e64 v75, v85, 0
	v_add_f32_e64 v74, v86, v74
	v_add_f32_e64 v75, v87, v75
	v_add_f32_e64 v74, v88, v74
	v_add_f32_e64 v75, v89, v75
	v_add_f32_e32 v74, v90, v74
	v_add_f32_e32 v75, v91, v75
	s_nop 0
	v_add_f32_e32 v74, v92, v74
	v_add_f32_e32 v75, v93, v75
	s_nop 0
	v_add_f32_e32 v74, v94, v74
	v_add_f32_e32 v75, v95, v75
	s_nop 0
	v_add_f32_e32 v74, v96, v74
	v_add_f32_e32 v75, v97, v75
	s_nop 0
	v_add_f32_e32 v74, v98, v74
	v_add_f32_e32 v75, v99, v75
	s_nop 0
	v_add_f32_e32 v68, v68, v74
	v_add_f32_e32 v69, v69, v75
	s_nop 0
	v_add_f32_e32 v68, v70, v68
	v_add_f32_e32 v69, v71, v69
	s_nop 0
	v_add_f32_e32 v68, v72, v68
	v_add_f32_e32 v69, v73, v69
	s_nop 0
	v_add_f32_e32 v68, v228, v68
	v_add_f32_e32 v69, v229, v69
	s_nop 0
	v_add_f32_e32 v68, v230, v68
	v_add_f32_e32 v69, v231, v69
	s_nop 0
	v_add_f32_e32 v68, v232, v68
	v_add_f32_e32 v69, v233, v69
	s_nop 0
	v_add_f32_e32 v68, v234, v68
	v_add_f32_e32 v69, v235, v69
	s_nop 0
	v_add_f32_e32 v68, v82, v68
	v_add_f32_e32 v69, v83, v69
	s_nop 0
	v_add_f32_e32 v3, v68, v69
	s_waitcnt lgkmcnt(0)
	v_mov_b32_e32 v68, v3
	s_nop 1
	v_permlane32_swap_b32_e32 v68, v3
	v_add_f32_e32 v3, v3, v68
	v_fmac_f32_e32 v3, v217, v170

.LBB0_1427:
	v_sub_u32_e32 v68, v161, v165
	s_cmp_gt_i32 s42, s76
	v_cvt_f32_i32_e32 v220, v68
	s_cselect_b64 s[2:3], -1, 0
	s_and_b64 s[8:9], s[24:25], s[2:3]
	v_add_u32_e32 v69, s38, v176
	s_mov_b64 s[2:3], -1
	s_andn2_b64 vcc, exec, s[8:9]
	v_add_u32_e32 v219, v69, v177
	v_add_u32_e32 v165, v69, v178
	s_cbranch_vccz .LBB0_1431
	v_mov_b32_e32 v3, v157
	ds_read_b128 v[52:55], v219
	ds_read_b128 v[56:59], v219 offset:32
	v_mul_f32_e64 v66, v220, -v3
	v_mov_b32_e32 v78, v3
	v_fma_f32 v38, 0, v3, v66
	v_fmamk_f32 v42, v3, 0x41000000, v66
	v_fmamk_f32 v46, v3, 0x41800000, v66
	v_fmamk_f32 v50, v3, 0x41c00000, v66
	v_add_f32_e32 v36, v2, v38
	v_add_f32_e32 v37, v3, v38
	v_fma_f32 v39, v78, s65, v38
	v_fma_f32 v38, v78, s64, v38
	v_add_f32_e32 v40, v2, v42
	v_add_f32_e32 v41, v3, v42
	v_fma_f32 v43, v78, s65, v42
	v_fma_f32 v42, v78, s64, v42
	v_add_f32_e32 v44, v2, v46
	v_add_f32_e32 v45, v3, v46
	v_fma_f32 v47, v78, s65, v46
	v_fma_f32 v46, v78, s64, v46
	v_add_f32_e32 v48, v2, v50
	v_add_f32_e32 v49, v3, v50
	v_fma_f32 v51, v78, s65, v50
	v_fma_f32 v50, v78, s64, v50
	v_fmamk_f32 v60, v3, 0x42200000, v66
	v_fmamk_f32 v62, v3, 0x42400000, v66
	s_waitcnt lgkmcnt(1)
	v_mfma_f32_32x32x16_bf16 v[36:51], v[52:55], v[100:103], v[36:51]
	v_cmp_gt_u32_e32 vcc, s47, v68
	s_waitcnt lgkmcnt(0)
	v_mfma_f32_32x32x16_bf16 v[36:51], v[56:59], v[104:107], v[36:51]
	ds_read_b128 v[52:55], v219 offset:64
	ds_read_b128 v[56:59], v219 offset:96
	ds_read_b128 v[70:73], v165
	ds_read_b128 v[74:77], v165 offset:32
	s_waitcnt lgkmcnt(3)
	v_mfma_f32_32x32x16_bf16 v[36:51], v[52:55], v[108:111], v[36:51]
	v_fmamk_f32 v54, v3, 0x42000000, v66
	v_fmac_f32_e32 v66, 0x42600000, v3
	v_add_f32_e64 v52, v2, v54
	v_add_f32_e64 v53, v3, v54
	v_fma_f32 v55, v78, s65, v54
	v_fma_f32 v54, v78, s64, v54
	v_add_f32_e32 v64, v2, v66
	v_add_f32_e32 v65, v3, v66
	v_fma_f32 v67, v78, s65, v66
	v_fma_f32 v66, v78, s64, v66
	s_waitcnt lgkmcnt(2)
	v_mfma_f32_32x32x16_bf16 v[36:51], v[56:59], v[112:115], v[36:51]
	v_add_f32_e64 v56, v2, v60
	v_add_f32_e64 v57, v3, v60
	v_fma_f32 v58, v78, s64, v60
	v_fma_f32 v59, v78, s65, v60
	v_add_f32_e64 v60, v2, v62
	v_add_f32_e64 v61, v3, v62
	v_fma_f32 v63, v78, s65, v62
	v_fma_f32 v62, v78, s64, v62
	v_add_u32_e32 v3, -1, v68
	s_nop 3
	v_cndmask_b32_e32 v88, v214, v36, vcc
	s_waitcnt lgkmcnt(1)
	v_mfma_f32_32x32x16_bf16 v[52:67], v[70:73], v[100:103], v[52:67]
	ds_read_b128 v[70:73], v165 offset:64
	ds_read_b128 v[78:81], v165 offset:96
	v_cmp_gt_u32_e32 vcc, s47, v3
	v_add_u32_e32 v36, -2, v68
	s_nop 0
	v_cndmask_b32_e32 v89, v214, v37, vcc
	v_cmp_gt_u32_e32 vcc, s47, v36
	v_add_u32_e32 v36, -3, v68
	s_waitcnt lgkmcnt(2)
	v_mfma_f32_32x32x16_bf16 v[52:67], v[74:77], v[104:107], v[52:67]
	v_cndmask_b32_e32 v94, v214, v38, vcc
	v_cmp_gt_u32_e32 vcc, s47, v36
	v_add_u32_e32 v36, -8, v68
	v_max3_f32 v3, v88, s97, v89
	v_cndmask_b32_e32 v95, v214, v39, vcc
	v_cmp_gt_u32_e32 vcc, s47, v36
	v_add_u32_e32 v36, -9, v68
	s_waitcnt lgkmcnt(1)
	v_mfma_f32_32x32x16_bf16 v[52:67], v[70:73], v[108:111], v[52:67]
	v_cndmask_b32_e32 v96, v214, v40, vcc
	v_cmp_gt_u32_e32 vcc, s47, v36
	v_add_u32_e32 v36, -10, v68
	v_max3_f32 v3, v3, v94, v95
	v_cndmask_b32_e32 v97, v214, v41, vcc
	v_cmp_gt_u32_e32 vcc, s47, v36
	v_add_u32_e32 v36, -11, v68
	s_waitcnt lgkmcnt(0)
	v_mfma_f32_32x32x16_bf16 v[52:67], v[78:81], v[112:115], v[52:67]
	v_cndmask_b32_e32 v98, v214, v42, vcc
	v_cmp_gt_u32_e32 vcc, s47, v36
	v_add_u32_e32 v36, -16, v68
	v_max3_f32 v3, v3, v96, v97
	v_cndmask_b32_e32 v99, v214, v43, vcc
	v_cmp_gt_u32_e32 vcc, s47, v36
	v_subrev_u32_e32 v36, 17, v68
	v_max3_f32 v3, v3, v98, v99
	v_cndmask_b32_e32 v170, v214, v44, vcc
	v_cmp_gt_u32_e32 vcc, s47, v36
	v_subrev_u32_e32 v36, 18, v68
	s_nop 0
	v_cndmask_b32_e32 v171, v214, v45, vcc
	v_cmp_gt_u32_e32 vcc, s47, v36
	v_subrev_u32_e32 v36, 19, v68
	v_max3_f32 v3, v3, v170, v171
	v_cndmask_b32_e32 v90, v214, v46, vcc
	v_cmp_gt_u32_e32 vcc, s47, v36
	v_subrev_u32_e32 v36, 24, v68
	s_nop 0
	v_cndmask_b32_e32 v91, v214, v47, vcc
	v_cmp_gt_u32_e32 vcc, s47, v36
	v_subrev_u32_e32 v36, 25, v68
	v_max3_f32 v3, v3, v90, v91
	v_cndmask_b32_e32 v92, v214, v48, vcc
	v_cmp_gt_u32_e32 vcc, s47, v36
	v_subrev_u32_e32 v36, 26, v68
	s_nop 0
	v_cndmask_b32_e32 v93, v214, v49, vcc
	v_cmp_gt_u32_e32 vcc, s47, v36
	v_subrev_u32_e32 v36, 27, v68
	v_max3_f32 v3, v3, v92, v93
	v_cndmask_b32_e32 v86, v214, v50, vcc
	v_cmp_gt_u32_e32 vcc, s47, v36
	v_subrev_u32_e32 v36, 32, v68
	s_nop 0
	v_cndmask_b32_e32 v87, v214, v51, vcc
	v_cmp_gt_u32_e32 vcc, s47, v36
	v_subrev_u32_e32 v36, 33, v68
	v_max3_f32 v3, v3, v86, v87
	v_cndmask_b32_e32 v76, v214, v52, vcc
	v_cmp_gt_u32_e32 vcc, s47, v36
	v_subrev_u32_e32 v36, 34, v68
	s_nop 0
	v_cndmask_b32_e32 v77, v214, v53, vcc
	v_cmp_gt_u32_e32 vcc, s47, v36
	v_subrev_u32_e32 v36, 35, v68
	v_max3_f32 v3, v3, v76, v77
	v_cndmask_b32_e32 v78, v214, v54, vcc
	v_cmp_gt_u32_e32 vcc, s47, v36
	v_subrev_u32_e32 v36, 40, v68
	s_nop 0
	v_cndmask_b32_e32 v79, v214, v55, vcc
	v_cmp_gt_u32_e32 vcc, s47, v36
	v_subrev_u32_e32 v36, 41, v68
	v_max3_f32 v3, v3, v78, v79
	v_cndmask_b32_e32 v80, v214, v56, vcc
	v_cmp_gt_u32_e32 vcc, s47, v36
	v_subrev_u32_e32 v36, 42, v68
	s_nop 0
	v_cndmask_b32_e32 v81, v214, v57, vcc
	v_cmp_gt_u32_e32 vcc, s47, v36
	v_subrev_u32_e32 v36, 43, v68
	v_max3_f32 v3, v3, v80, v81
	v_cndmask_b32_e32 v82, v214, v58, vcc
	v_cmp_gt_u32_e32 vcc, s47, v36
	v_subrev_u32_e32 v36, 48, v68
	s_nop 0
	v_cndmask_b32_e32 v83, v214, v59, vcc
	v_cmp_gt_u32_e32 vcc, s47, v36
	v_subrev_u32_e32 v36, 49, v68
	v_max3_f32 v3, v3, v82, v83
	v_cndmask_b32_e32 v84, v214, v60, vcc
	v_cmp_gt_u32_e32 vcc, s47, v36
	v_subrev_u32_e32 v36, 50, v68
	s_nop 0
	v_cndmask_b32_e32 v85, v214, v61, vcc
	v_cmp_gt_u32_e32 vcc, s47, v36
	v_subrev_u32_e32 v36, 51, v68
	v_max3_f32 v3, v3, v84, v85
	v_cndmask_b32_e32 v74, v214, v62, vcc
	v_cmp_gt_u32_e32 vcc, s47, v36
	v_subrev_u32_e32 v36, 56, v68
	s_nop 0
	v_cndmask_b32_e32 v75, v214, v63, vcc
	v_cmp_gt_u32_e32 vcc, s47, v36
	v_subrev_u32_e32 v36, 57, v68
	v_max3_f32 v3, v3, v74, v75
	v_cndmask_b32_e32 v70, v214, v64, vcc
	v_cmp_gt_u32_e32 vcc, s47, v36
	v_subrev_u32_e32 v36, 58, v68
	s_nop 0
	v_cndmask_b32_e32 v71, v214, v65, vcc
	v_cmp_gt_u32_e32 vcc, s47, v36
	v_subrev_u32_e32 v36, 59, v68
	v_max3_f32 v3, v3, v70, v71
	v_cndmask_b32_e32 v72, v214, v66, vcc
	v_cmp_gt_u32_e32 vcc, s47, v36
	s_nop 1
	v_cndmask_b32_e32 v73, v214, v67, vcc
	v_max3_f32 v3, v3, v72, v73
	s_nop 3
	s_waitcnt lgkmcnt(0)
	v_mov_b32_e32 v36, v3
	s_nop 1
	v_permlane32_swap_b32_e32 v36, v3
	v_max_f32_e32 v36, v36, v36
	v_max_f32_e32 v3, v3, v36
	v_max3_f32 v132, v218, v3, s46
	v_sub_f32_e32 v3, v218, v132
	v_exp_f32_e32 v68, v3
	s_nop 2
	v_cmp_eq_f32_e32 vcc, 1.0, v68
	s_cmp_eq_u64 vcc, exec
	s_nop 8
	s_cbranch_scc1 .LBB0_1430
	v_mul_f32_e32 v34, v34, v68
	v_mul_f32_e32 v35, v35, v68
	v_mul_f32_e32 v32, v32, v68
	v_mul_f32_e32 v33, v33, v68
	v_mul_f32_e32 v30, v30, v68
	v_mul_f32_e32 v31, v31, v68
	v_mul_f32_e32 v28, v28, v68
	v_mul_f32_e32 v29, v29, v68
	v_mul_f32_e32 v26, v26, v68
	v_mul_f32_e32 v27, v27, v68
	v_mul_f32_e32 v24, v24, v68
	v_mul_f32_e32 v25, v25, v68
	v_mul_f32_e32 v22, v22, v68
	v_mul_f32_e32 v23, v23, v68
	v_mul_f32_e32 v20, v20, v68
	v_mul_f32_e32 v21, v21, v68
	v_mul_f32_e32 v18, v18, v68
	v_mul_f32_e32 v19, v19, v68
	v_mul_f32_e32 v16, v16, v68
	v_mul_f32_e32 v17, v17, v68
	v_mul_f32_e32 v14, v14, v68
	v_mul_f32_e32 v15, v15, v68
	v_mul_f32_e32 v12, v12, v68
	v_mul_f32_e32 v13, v13, v68
	v_mul_f32_e32 v10, v10, v68
	v_mul_f32_e32 v11, v11, v68
	v_mul_f32_e32 v8, v8, v68
	v_mul_f32_e32 v9, v9, v68
	v_mul_f32_e32 v6, v6, v68
	v_mul_f32_e32 v7, v7, v68
	v_mul_f32_e32 v4, v4, v68
	v_mul_f32_e32 v5, v5, v68
.LBB0_1430:
	v_sub_f32_e32 v94, v94, v132
	v_sub_f32_e32 v95, v95, v132
	v_lshl_add_u32 v3, v136, 1, s38
	v_exp_f32_e32 v230, v94
	v_exp_f32_e32 v231, v95
	v_sub_f32_e32 v94, v96, v132
	v_sub_f32_e32 v95, v97, v132
	v_sub_f32_e32 v88, v88, v132
	v_sub_f32_e32 v89, v89, v132
	v_exp_f32_e32 v232, v94
	v_exp_f32_e32 v233, v95
	v_sub_f32_e32 v94, v98, v132
	v_sub_f32_e32 v95, v99, v132
	v_exp_f32_e32 v88, v88
	v_exp_f32_e32 v98, v94
	v_add_u32_e32 v94, v3, v190
	v_add_u32_e32 v186, 0x2000, v94
	v_exp_f32_e32 v99, v95
	ds_read2_b64 v[94:97], v186 offset0:128 offset1:130
	v_add_u32_e32 v3, v3, v191
	v_add_u32_e32 v3, 0x2000, v3
	ds_read2_b64 v[226:229], v3 offset0:128 offset1:130
	v_exp_f32_e32 v89, v89
	v_sub_f32_e32 v90, v90, v132
	v_sub_f32_e32 v91, v91, v132
	v_cvt_pk_bf16_f32 v223, v230, v231
	v_exp_f32_e32 v234, v90
	v_exp_f32_e32 v235, v91
	v_sub_f32_e32 v90, v92, v132
	v_sub_f32_e32 v91, v93, v132
	v_cvt_pk_bf16_f32 v222, v88, v89
	v_cvt_pk_bf16_f32 v224, v232, v233
	v_cvt_pk_bf16_f32 v225, v98, v99
	v_exp_f32_e32 v236, v90
	v_exp_f32_e32 v237, v91
	ds_read2_b64 v[90:93], v186 offset0:132 offset1:134
	s_waitcnt lgkmcnt(2)
	v_mfma_f32_32x32x16_bf16 v[20:35], v[94:97], v[222:225], v[20:35]
	v_add_f32_e64 v170, v170, -v132
	v_add_f32_e64 v171, v171, -v132
	v_add_f32_e64 v86, v86, -v132
	v_add_f32_e64 v87, v87, -v132
	v_exp_f32_e32 v170, v170
	v_exp_f32_e32 v171, v171
	v_cvt_pk_bf16_f32 v95, v234, v235
	v_cvt_pk_bf16_f32 v96, v236, v237
	v_cvt_pk_bf16_f32 v94, v170, v171
	s_waitcnt lgkmcnt(1)
	v_mfma_f32_32x32x16_bf16 v[4:19], v[226:229], v[222:225], v[4:19]
	v_exp_f32_e32 v222, v86
	v_exp_f32_e32 v223, v87
	s_nop 0
	v_cvt_pk_bf16_f32 v97, v222, v223
	s_waitcnt lgkmcnt(0)
	s_nop 0
	v_mfma_f32_32x32x16_bf16 v[20:35], v[90:93], v[94:97], v[20:35]
	ds_read2_b64 v[90:93], v3 offset0:132 offset1:134
	s_waitcnt lgkmcnt(0)
	v_mfma_f32_32x32x16_bf16 v[4:19], v[90:93], v[94:97], v[4:19]
	v_add_f32_e64 v76, v76, -v132
	v_add_f32_e64 v77, v77, -v132
	v_add_f32_e64 v74, v74, -v132
	v_add_f32_e64 v75, v75, -v132
	v_exp_f32_e32 v90, v76
	v_exp_f32_e32 v91, v77
	v_sub_f32_e32 v76, v78, v132
	v_sub_f32_e32 v77, v79, v132
	v_sub_f32_e32 v70, v70, v132
	v_sub_f32_e32 v71, v71, v132
	v_exp_f32_e32 v92, v76
	v_exp_f32_e32 v93, v77
	v_sub_f32_e32 v76, v80, v132
	v_sub_f32_e32 v77, v81, v132
	v_sub_f32_e32 v80, v84, v132
	v_sub_f32_e32 v81, v85, v132
	v_exp_f32_e32 v94, v76
	v_exp_f32_e32 v95, v77
	v_sub_f32_e32 v76, v82, v132
	v_sub_f32_e32 v77, v83, v132
	ds_read2_b64 v[84:87], v3 offset0:136 offset1:138
	v_exp_f32_e32 v96, v76
	v_exp_f32_e32 v97, v77
	ds_read2_b64 v[76:79], v186 offset0:136 offset1:138
	v_exp_f32_e32 v224, v80
	v_exp_f32_e32 v225, v81
	v_cvt_pk_bf16_f32 v80, v90, v91
	v_cvt_pk_bf16_f32 v81, v92, v93
	v_cvt_pk_bf16_f32 v82, v94, v95
	v_cvt_pk_bf16_f32 v83, v96, v97
	v_exp_f32_e32 v226, v74
	v_exp_f32_e32 v227, v75
	v_exp_f32_e32 v228, v70
	v_exp_f32_e32 v229, v71
	v_sub_f32_e32 v74, v72, v132
	v_sub_f32_e32 v75, v73, v132
	ds_read2_b64 v[70:73], v186 offset0:140 offset1:142
	s_waitcnt lgkmcnt(1)
	v_mfma_f32_32x32x16_bf16 v[20:35], v[76:79], v[80:83], v[20:35]
	v_cvt_pk_bf16_f32 v78, v224, v225
	v_cvt_pk_bf16_f32 v79, v226, v227
	s_mov_b64 s[2:3], 0
	v_mfma_f32_32x32x16_bf16 v[4:19], v[84:87], v[80:83], v[4:19]
	v_exp_f32_e32 v82, v74
	v_exp_f32_e32 v83, v75
	v_cvt_pk_bf16_f32 v80, v228, v229
	ds_read2_b64 v[74:77], v3 offset0:140 offset1:142
	v_cvt_pk_bf16_f32 v81, v82, v83
	s_waitcnt lgkmcnt(1)
	s_nop 0
	v_mfma_f32_32x32x16_bf16 v[20:35], v[70:73], v[78:81], v[20:35]
	v_add_f32_e64 v70, v88, 0
	v_add_f32_e64 v71, v89, 0
	v_add_f32_e64 v70, v230, v70
	v_add_f32_e64 v71, v231, v71
	v_add_f32_e64 v70, v232, v70
	v_add_f32_e64 v71, v233, v71
	v_add_f32_e32 v70, v98, v70
	v_add_f32_e32 v71, v99, v71
	s_waitcnt lgkmcnt(0)
	v_mfma_f32_32x32x16_bf16 v[4:19], v[74:77], v[78:81], v[4:19]
	v_add_f32_e64 v70, v170, v70
	v_add_f32_e64 v71, v171, v71
	v_add_f32_e64 v70, v234, v70
	v_add_f32_e64 v71, v235, v71
	v_add_f32_e64 v70, v236, v70
	v_add_f32_e64 v71, v237, v71
	v_add_f32_e32 v70, v222, v70
	v_add_f32_e32 v71, v223, v71
	s_nop 0
	v_add_f32_e32 v70, v90, v70
	v_add_f32_e32 v71, v91, v71
	s_nop 0
	v_add_f32_e32 v70, v92, v70
	v_add_f32_e32 v71, v93, v71
	s_nop 0
	v_add_f32_e32 v70, v94, v70
	v_add_f32_e32 v71, v95, v71
	s_nop 0
	v_add_f32_e32 v70, v96, v70
	v_add_f32_e32 v71, v97, v71
	s_nop 0
	v_add_f32_e32 v70, v224, v70
	v_add_f32_e32 v71, v225, v71
	s_nop 0
	v_add_f32_e32 v70, v226, v70
	v_add_f32_e32 v71, v227, v71
	s_nop 0
	v_add_f32_e32 v70, v228, v70
	v_add_f32_e32 v71, v229, v71
	s_nop 0
	v_add_f32_e32 v70, v82, v70
	v_add_f32_e32 v71, v83, v71
	s_nop 0
	v_add_f32_e32 v3, v70, v71
	s_waitcnt lgkmcnt(0)
	v_mov_b32_e32 v70, v3
	s_nop 1
	v_permlane32_swap_b32_e32 v70, v3
	v_add_f32_e32 v3, v3, v70
	v_fmac_f32_e32 v3, v217, v68
.LBB0_1431:
	s_and_b64 vcc, exec, s[2:3]
	s_cbranch_vccz .LBB0_1442
	v_mov_b32_e32 v3, v157
	s_nop 0
	v_mul_f32_e64 v50, v220, -v3
	v_mov_b32_e32 v68, v3
	v_fma_f32 v36, 0, v3, v50
	v_add_f32_e32 v52, v2, v36
	v_add_f32_e32 v53, v3, v36
	v_fma_f32 v54, v68, s64, v36
	v_fma_f32 v55, v68, s65, v36
	v_fmamk_f32 v36, v3, 0x41000000, v50
	v_add_f32_e32 v56, v2, v36
	v_add_f32_e32 v57, v3, v36
	v_fma_f32 v58, v68, s64, v36
	v_fma_f32 v59, v68, s65, v36
	v_fmamk_f32 v36, v3, 0x41800000, v50
	v_add_f32_e32 v60, v2, v36
	v_add_f32_e32 v61, v3, v36
	v_fma_f32 v62, v68, s64, v36
	v_fma_f32 v63, v68, s65, v36
	v_fmamk_f32 v36, v3, 0x41c00000, v50
	v_add_f32_e32 v64, v2, v36
	v_add_f32_e32 v65, v3, v36
	v_fma_f32 v66, v68, s64, v36
	v_fma_f32 v67, v68, s65, v36
	ds_read_b128 v[36:39], v219
	ds_read_b128 v[40:43], v219 offset:32
	s_waitcnt lgkmcnt(1)
	v_mfma_f32_32x32x16_bf16 v[52:67], v[36:39], v[100:103], v[52:67]
	ds_read_b128 v[36:39], v219 offset:64
	v_fmamk_f32 v46, v3, 0x42400000, v50
	v_add_f32_e64 v44, v2, v46
	v_add_f32_e64 v45, v3, v46
	v_fma_f32 v47, v68, s65, v46
	v_fma_f32 v46, v68, s64, v46
	s_waitcnt lgkmcnt(1)
	v_mfma_f32_32x32x16_bf16 v[52:67], v[40:43], v[104:107], v[52:67]
	v_fmamk_f32 v42, v3, 0x42200000, v50
	v_add_f32_e64 v40, v2, v42
	v_add_f32_e64 v41, v3, v42
	v_fma_f32 v43, v68, s65, v42
	v_fma_f32 v42, v68, s64, v42
	s_waitcnt lgkmcnt(0)
	v_mfma_f32_32x32x16_bf16 v[52:67], v[36:39], v[108:111], v[52:67]
	ds_read_b128 v[36:39], v219 offset:96
	ds_read_b128 v[70:73], v165
	ds_read_b128 v[74:77], v165 offset:32
	s_waitcnt lgkmcnt(2)
	v_mfma_f32_32x32x16_bf16 v[52:67], v[36:39], v[112:115], v[52:67]
	v_fmamk_f32 v38, v3, 0x42000000, v50
	v_fmac_f32_e32 v50, 0x42600000, v3
	v_add_f32_e64 v36, v2, v38
	v_add_f32_e64 v37, v3, v38
	v_fma_f32 v39, v68, s65, v38
	v_fma_f32 v38, v68, s64, v38
	v_add_f32_e32 v48, v2, v50
	v_add_f32_e32 v49, v3, v50
	v_fma_f32 v51, v68, s65, v50
	v_fma_f32 v50, v68, s64, v50
	s_nop 4
	v_max3_f32 v3, v52, s97, v53
	s_waitcnt lgkmcnt(1)
	v_mfma_f32_32x32x16_bf16 v[36:51], v[70:73], v[100:103], v[36:51]
	ds_read_b128 v[70:73], v165 offset:64
	v_max3_f32 v3, v3, v54, v55
	v_max3_f32 v3, v3, v56, v57
	v_max3_f32 v3, v3, v58, v59
	v_max3_f32 v3, v3, v60, v61
	v_max3_f32 v3, v3, v62, v63
	v_max3_f32 v3, v3, v64, v65
	s_waitcnt lgkmcnt(1)
	v_mfma_f32_32x32x16_bf16 v[36:51], v[74:77], v[104:107], v[36:51]
	v_max3_f32 v3, v3, v66, v67
	s_waitcnt lgkmcnt(0)
	v_mfma_f32_32x32x16_bf16 v[36:51], v[70:73], v[108:111], v[36:51]
	ds_read_b128 v[70:73], v165 offset:96
	s_waitcnt lgkmcnt(0)
	v_mfma_f32_32x32x16_bf16 v[36:51], v[70:73], v[112:115], v[36:51]
	s_nop 11
	v_max3_f32 v3, v3, v36, v37
	v_max3_f32 v3, v3, v38, v39
	v_max3_f32 v3, v3, v40, v41
	v_max3_f32 v3, v3, v42, v43
	v_max3_f32 v3, v3, v44, v45
	v_max3_f32 v3, v3, v46, v47
	v_max3_f32 v3, v3, v48, v49
	v_max3_f32 v3, v3, v50, v51
	s_waitcnt lgkmcnt(0)
	v_mov_b32_e32 v68, v3
	s_nop 1
	v_permlane32_swap_b32_e32 v68, v3
	v_max_f32_e32 v68, v68, v68
	v_max_f32_e32 v3, v3, v68
	v_max3_f32 v132, v218, v3, s46
	v_sub_f32_e32 v3, v218, v132
	v_exp_f32_e32 v68, v3
	s_nop 0
	v_cmp_eq_f32_e32 vcc, 1.0, v68
	s_cmp_eq_u64 vcc, exec
	s_cbranch_scc1 .LBB0_1434
	v_mul_f32_e32 v34, v34, v68
	v_mul_f32_e32 v35, v35, v68
	v_mul_f32_e32 v32, v32, v68
	v_mul_f32_e32 v33, v33, v68
	v_mul_f32_e32 v30, v30, v68
	v_mul_f32_e32 v31, v31, v68
	v_mul_f32_e32 v28, v28, v68
	v_mul_f32_e32 v29, v29, v68
	v_mul_f32_e32 v26, v26, v68
	v_mul_f32_e32 v27, v27, v68
	v_mul_f32_e32 v24, v24, v68
	v_mul_f32_e32 v25, v25, v68
	v_mul_f32_e32 v22, v22, v68
	v_mul_f32_e32 v23, v23, v68
	v_mul_f32_e32 v20, v20, v68
	v_mul_f32_e32 v21, v21, v68
	v_mul_f32_e32 v18, v18, v68
	v_mul_f32_e32 v19, v19, v68
	v_mul_f32_e32 v16, v16, v68
	v_mul_f32_e32 v17, v17, v68
	v_mul_f32_e32 v14, v14, v68
	v_mul_f32_e32 v15, v15, v68
	v_mul_f32_e32 v12, v12, v68
	v_mul_f32_e32 v13, v13, v68
	v_mul_f32_e32 v10, v10, v68
	v_mul_f32_e32 v11, v11, v68
	v_mul_f32_e32 v8, v8, v68
	v_mul_f32_e32 v9, v9, v68
	v_mul_f32_e32 v6, v6, v68
	v_mul_f32_e32 v7, v7, v68
	v_mul_f32_e32 v4, v4, v68
	v_mul_f32_e32 v5, v5, v68
.LBB0_1434:
	v_add_u32_e32 v3, v69, v196
	v_sub_f32_e32 v52, v52, v132
	v_sub_f32_e32 v53, v53, v132
	v_sub_f32_e32 v54, v54, v132
	v_sub_f32_e32 v55, v55, v132
	v_sub_f32_e32 v56, v56, v132
	v_sub_f32_e32 v57, v57, v132
	v_sub_f32_e32 v58, v58, v132
	v_sub_f32_e32 v59, v59, v132
	v_add_u32_e32 v69, v3, v190
	v_exp_f32_e32 v52, v52
	v_exp_f32_e32 v53, v53
	v_exp_f32_e32 v54, v54
	v_exp_f32_e32 v55, v55
	v_exp_f32_e32 v56, v56
	v_exp_f32_e32 v57, v57
	v_exp_f32_e32 v58, v58
	v_exp_f32_e32 v59, v59
	v_add_u32_e32 v69, 0x2000, v69
	ds_read2_b64 v[74:77], v69 offset0:128 offset1:130
	ds_read2_b64 v[78:81], v69 offset0:132 offset1:134
	v_add_u32_e32 v3, v3, v191
	v_cvt_pk_bf16_f32 v70, v52, v53
	v_cvt_pk_bf16_f32 v71, v54, v55
	v_cvt_pk_bf16_f32 v72, v56, v57
	v_cvt_pk_bf16_f32 v73, v58, v59
	v_add_u32_e32 v3, 0x2000, v3
	v_sub_f32_e32 v60, v60, v132
	v_sub_f32_e32 v61, v61, v132
	s_waitcnt lgkmcnt(1)
	v_mfma_f32_32x32x16_bf16 v[20:35], v[74:77], v[70:73], v[20:35]
	ds_read2_b64 v[74:77], v3 offset0:128 offset1:130
	ds_read2_b64 v[82:85], v3 offset0:132 offset1:134
	v_add_f32_e64 v62, v62, -v132
	v_add_f32_e64 v63, v63, -v132
	v_add_f32_e64 v64, v64, -v132
	v_add_f32_e64 v65, v65, -v132
	v_sub_f32_e32 v66, v66, v132
	v_sub_f32_e32 v67, v67, v132
	v_exp_f32_e32 v60, v60
	v_exp_f32_e32 v61, v61
	v_exp_f32_e32 v62, v62
	s_waitcnt lgkmcnt(1)
	v_mfma_f32_32x32x16_bf16 v[4:19], v[74:77], v[70:73], v[4:19]
	v_exp_f32_e32 v63, v63
	v_exp_f32_e32 v64, v64
	v_exp_f32_e32 v65, v65
	v_exp_f32_e32 v66, v66
	v_exp_f32_e32 v67, v67
	v_cvt_pk_bf16_f32 v70, v60, v61
	v_cvt_pk_bf16_f32 v71, v62, v63
	v_cvt_pk_bf16_f32 v72, v64, v65
	v_cvt_pk_bf16_f32 v73, v66, v67
	s_nop 1
	v_mfma_f32_32x32x16_bf16 v[20:35], v[78:81], v[70:73], v[20:35]
	s_waitcnt lgkmcnt(0)
	v_mfma_f32_32x32x16_bf16 v[4:19], v[82:85], v[70:73], v[4:19]
	v_add_f32_e64 v42, v42, -v132
	v_add_f32_e64 v43, v43, -v132
	v_add_f32_e64 v36, v36, -v132
	v_add_f32_e64 v37, v37, -v132
	v_add_f32_e64 v38, v38, -v132
	v_add_f32_e64 v39, v39, -v132
	v_sub_f32_e32 v40, v40, v132
	v_sub_f32_e32 v41, v41, v132
	v_exp_f32_e32 v78, v42
	v_exp_f32_e32 v79, v43
	v_sub_f32_e32 v42, v44, v132
	v_sub_f32_e32 v43, v45, v132
	v_exp_f32_e32 v36, v36
	v_exp_f32_e32 v37, v37
	v_exp_f32_e32 v38, v38
	v_exp_f32_e32 v39, v39
	v_exp_f32_e32 v40, v40
	v_exp_f32_e32 v41, v41
	v_exp_f32_e32 v80, v42
	v_exp_f32_e32 v81, v43
	v_sub_f32_e32 v42, v46, v132
	v_sub_f32_e32 v43, v47, v132
	v_cvt_pk_bf16_f32 v44, v40, v41
	v_exp_f32_e32 v82, v42
	v_exp_f32_e32 v83, v43
	v_sub_f32_e32 v42, v48, v132
	v_sub_f32_e32 v43, v49, v132
	ds_read2_b64 v[46:49], v69 offset0:136 offset1:138
	ds_read2_b64 v[70:73], v69 offset0:140 offset1:142
	v_exp_f32_e32 v84, v42
	v_exp_f32_e32 v85, v43
	v_sub_f32_e32 v42, v50, v132
	v_sub_f32_e32 v43, v51, v132
	v_cvt_pk_bf16_f32 v45, v78, v79
	v_exp_f32_e32 v50, v42
	v_exp_f32_e32 v51, v43
	v_cvt_pk_bf16_f32 v42, v36, v37
	v_cvt_pk_bf16_f32 v43, v38, v39
	s_waitcnt lgkmcnt(1)
	s_nop 0
	v_mfma_f32_32x32x16_bf16 v[20:35], v[46:49], v[42:45], v[20:35]
	ds_read2_b64 v[46:49], v3 offset0:136 offset1:138
	ds_read2_b64 v[74:77], v3 offset0:140 offset1:142
	s_waitcnt lgkmcnt(1)
	v_mfma_f32_32x32x16_bf16 v[4:19], v[46:49], v[42:45], v[4:19]
	v_cvt_pk_bf16_f32 v42, v80, v81
	v_cvt_pk_bf16_f32 v43, v82, v83
	v_cvt_pk_bf16_f32 v44, v84, v85
	v_cvt_pk_bf16_f32 v45, v50, v51
	s_nop 1
	v_mfma_f32_32x32x16_bf16 v[20:35], v[70:73], v[42:45], v[20:35]
	s_waitcnt lgkmcnt(0)
	v_mfma_f32_32x32x16_bf16 v[4:19], v[74:77], v[42:45], v[4:19]
	v_add_f32_e64 v42, v52, 0
	v_add_f32_e64 v43, v53, 0
	v_add_f32_e64 v42, v54, v42
	v_add_f32_e64 v43, v55, v43
	v_add_f32_e64 v42, v56, v42
	v_add_f32_e64 v43, v57, v43
	v_add_f32_e32 v42, v58, v42
	v_add_f32_e32 v43, v59, v43
	s_nop 0
	v_add_f32_e32 v42, v60, v42
	v_add_f32_e32 v43, v61, v43
	s_nop 0
	v_add_f32_e32 v42, v62, v42
	v_add_f32_e32 v43, v63, v43
	s_nop 0
	v_add_f32_e32 v42, v64, v42
	v_add_f32_e32 v43, v65, v43
	s_nop 0
	v_add_f32_e32 v42, v66, v42
	v_add_f32_e32 v43, v67, v43
	s_nop 0
	v_add_f32_e32 v36, v36, v42
	v_add_f32_e32 v37, v37, v43
	s_nop 0
	v_add_f32_e32 v36, v38, v36
	v_add_f32_e32 v37, v39, v37
	s_nop 0
	v_add_f32_e32 v36, v40, v36
	v_add_f32_e32 v37, v41, v37
	s_nop 0
	v_add_f32_e32 v36, v78, v36
	v_add_f32_e32 v37, v79, v37
	s_nop 0
	v_add_f32_e32 v36, v80, v36
	v_add_f32_e32 v37, v81, v37
	s_nop 0
	v_add_f32_e32 v36, v82, v36
	v_add_f32_e32 v37, v83, v37
	s_nop 0
	v_add_f32_e32 v36, v84, v36
	v_add_f32_e32 v37, v85, v37
	s_nop 0
	v_add_f32_e32 v36, v50, v36
	v_add_f32_e32 v37, v51, v37
	s_nop 0
	v_add_f32_e32 v3, v36, v37
	s_waitcnt lgkmcnt(0)
	v_mov_b32_e32 v36, v3
	s_nop 1
	v_permlane32_swap_b32_e32 v36, v3
	v_add_f32_e32 v3, v3, v36
	s_nop 0
	v_fmac_f32_e32 v3, v217, v68
	s_nop 6
	s_branch .LBB0_1442

.LBB0_1443:
	s_and_b64 vcc, exec, s[0:1]
	s_cbranch_vccnz .LBB0_1465
	v_lshrrev_b32_e32 v3, s39, v159
	v_and_b32_e32 v3, 1, v3
	v_cmp_eq_u32_e64 s[0:1], 1, v3
	s_or_b64 s[2:3], s[28:29], s[0:1]
	v_cndmask_b32_e64 v3, 0, 1, s[2:3]
	v_cmp_ne_u32_e32 vcc, 0, v3
	s_cbranch_vccz .LBB0_1465
	s_cmp_lt_i32 s39, s48
	s_cselect_b64 s[2:3], -1, 0
	s_cmp_ge_i32 s39, s48
	v_add_u32_e32 v165, s38, v176
	s_cselect_b64 s[26:27], -1, 0
	s_mov_b64 s[24:25], -1
	s_and_b64 vcc, exec, s[20:21]
	v_lshl_or_b32 v221, s39, 6, v136
	v_add_u32_e32 v220, v165, v177
	v_add_u32_e32 v219, v165, v178
	s_cbranch_vccz .LBB0_1454
	v_sub_u32_e32 v68, v161, v221
	v_cvt_f32_i32_e32 v69, v68
	s_and_b64 vcc, exec, s[26:27]
	s_cbranch_vccz .LBB0_1450
	v_mov_b32_e32 v3, v157
	ds_read_b128 v[52:55], v220 offset:17920
	ds_read_b128 v[56:59], v220 offset:17952
	v_mul_f32_e64 v36, v69, -v3
	v_cndmask_b32_e64 v66, v214, v36, s[0:1]
	v_mov_b32_e32 v74, v3
	v_fma_f32 v38, 0, v3, v66
	v_fmamk_f32 v42, v3, 0x41000000, v66
	v_fmamk_f32 v46, v3, 0x41800000, v66
	v_fmamk_f32 v50, v3, 0x41c00000, v66
	v_add_f32_e32 v36, v2, v38
	v_add_f32_e32 v37, v3, v38
	v_fma_f32 v39, v74, s65, v38
	v_fma_f32 v38, v74, s64, v38
	v_add_f32_e32 v40, v2, v42
	v_add_f32_e32 v41, v3, v42
	v_fma_f32 v43, v74, s65, v42
	v_fma_f32 v42, v74, s64, v42
	v_add_f32_e32 v44, v2, v46
	v_add_f32_e32 v45, v3, v46
	v_fma_f32 v47, v74, s65, v46
	v_fma_f32 v46, v74, s64, v46
	v_add_f32_e32 v48, v2, v50
	v_add_f32_e32 v49, v3, v50
	v_fma_f32 v51, v74, s65, v50
	v_fma_f32 v50, v74, s64, v50
	v_fmamk_f32 v62, v3, 0x42200000, v66
	v_fmamk_f32 v64, v3, 0x42400000, v66
	s_waitcnt lgkmcnt(1)
	v_mfma_f32_32x32x16_bf16 v[36:51], v[52:55], v[100:103], v[36:51]
	v_cmp_lt_i32_e32 vcc, -1, v68
	s_waitcnt lgkmcnt(0)
	v_mfma_f32_32x32x16_bf16 v[36:51], v[56:59], v[104:107], v[36:51]
	ds_read_b128 v[52:55], v220 offset:17984
	ds_read_b128 v[58:61], v220 offset:18016
	ds_read_b128 v[70:73], v219 offset:17920
	v_add_f32_e64 v56, v2, v62
	v_add_f32_e64 v57, v3, v62
	s_waitcnt lgkmcnt(2)
	v_mfma_f32_32x32x16_bf16 v[36:51], v[52:55], v[108:111], v[36:51]
	v_fmamk_f32 v54, v3, 0x42000000, v66
	v_fmac_f32_e32 v66, 0x42600000, v3
	v_add_f32_e64 v52, v2, v54
	v_add_f32_e64 v53, v3, v54
	v_fma_f32 v55, v74, s65, v54
	v_fma_f32 v54, v74, s64, v54
	s_waitcnt lgkmcnt(1)
	v_mfma_f32_32x32x16_bf16 v[36:51], v[58:61], v[112:115], v[36:51]
	v_fma_f32 v58, v74, s64, v62
	v_fma_f32 v59, v74, s65, v62
	v_add_f32_e64 v60, v2, v64
	v_add_f32_e64 v61, v3, v64
	v_fma_f32 v62, v74, s64, v64
	v_fma_f32 v63, v74, s65, v64
	v_add_f32_e32 v64, v2, v66
	v_add_f32_e32 v65, v3, v66
	v_fma_f32 v67, v74, s65, v66
	v_fma_f32 v66, v74, s64, v66
	ds_read_b128 v[74:77], v219 offset:17952
	s_nop 2
	v_cndmask_b32_e32 v86, v214, v36, vcc
	s_waitcnt lgkmcnt(1)
	v_mfma_f32_32x32x16_bf16 v[52:67], v[70:73], v[100:103], v[52:67]
	ds_read_b128 v[70:73], v219 offset:17984
	ds_read_b128 v[78:81], v219 offset:18016
	v_cmp_lt_i32_e32 vcc, 0, v68
	s_nop 1
	v_cndmask_b32_e32 v87, v214, v37, vcc
	v_cmp_lt_i32_e32 vcc, 1, v68
	v_max3_f32 v3, v86, s97, v87
	s_waitcnt lgkmcnt(2)
	v_mfma_f32_32x32x16_bf16 v[52:67], v[74:77], v[104:107], v[52:67]
	v_cndmask_b32_e32 v94, v214, v38, vcc
	v_cmp_lt_i32_e32 vcc, 2, v68
	s_nop 1
	v_cndmask_b32_e32 v95, v214, v39, vcc
	v_cmp_lt_i32_e32 vcc, 7, v68
	v_max3_f32 v3, v3, v94, v95
	s_waitcnt lgkmcnt(1)
	v_mfma_f32_32x32x16_bf16 v[52:67], v[70:73], v[108:111], v[52:67]
	v_cndmask_b32_e32 v98, v214, v40, vcc
	v_cmp_lt_i32_e32 vcc, 8, v68
	s_nop 1
	v_cndmask_b32_e32 v99, v214, v41, vcc
	v_cmp_lt_i32_e32 vcc, 9, v68
	v_max3_f32 v3, v3, v98, v99
	s_waitcnt lgkmcnt(0)
	v_mfma_f32_32x32x16_bf16 v[52:67], v[78:81], v[112:115], v[52:67]
	v_cndmask_b32_e32 v96, v214, v42, vcc
	v_cmp_lt_i32_e32 vcc, 10, v68
	s_nop 1
	v_cndmask_b32_e32 v97, v214, v43, vcc
	v_cmp_lt_i32_e32 vcc, 15, v68
	v_max3_f32 v3, v3, v96, v97
	s_nop 0
	v_cndmask_b32_e32 v170, v214, v44, vcc
	v_cmp_lt_i32_e32 vcc, 16, v68
	s_nop 1
	v_cndmask_b32_e32 v171, v214, v45, vcc
	v_cmp_lt_i32_e32 vcc, 17, v68
	v_max3_f32 v3, v3, v170, v171
	s_nop 0
	v_cndmask_b32_e32 v90, v214, v46, vcc
	v_cmp_lt_i32_e32 vcc, 18, v68
	s_nop 1
	v_cndmask_b32_e32 v91, v214, v47, vcc
	v_cmp_lt_i32_e32 vcc, 23, v68
	v_max3_f32 v3, v3, v90, v91
	s_nop 0
	v_cndmask_b32_e32 v92, v214, v48, vcc
	v_cmp_lt_i32_e32 vcc, 24, v68
	s_nop 1
	v_cndmask_b32_e32 v93, v214, v49, vcc
	v_cmp_lt_i32_e32 vcc, 25, v68
	v_max3_f32 v3, v3, v92, v93
	s_nop 0
	v_cndmask_b32_e32 v88, v214, v50, vcc
	v_cmp_lt_i32_e32 vcc, 26, v68
	s_nop 1
	v_cndmask_b32_e32 v89, v214, v51, vcc
	v_cmp_lt_i32_e32 vcc, 31, v68
	v_max3_f32 v3, v3, v88, v89
	s_nop 0
	v_cndmask_b32_e32 v84, v214, v52, vcc
	v_cmp_lt_i32_e32 vcc, 32, v68
	s_nop 1
	v_cndmask_b32_e32 v85, v214, v53, vcc
	v_cmp_lt_i32_e32 vcc, 33, v68
	v_max3_f32 v3, v3, v84, v85
	s_nop 0
	v_cndmask_b32_e32 v82, v214, v54, vcc
	v_cmp_lt_i32_e32 vcc, 34, v68
	s_nop 1
	v_cndmask_b32_e32 v83, v214, v55, vcc
	v_cmp_lt_i32_e32 vcc, 39, v68
	v_max3_f32 v3, v3, v82, v83
	s_nop 0
	v_cndmask_b32_e32 v80, v214, v56, vcc
	v_cmp_lt_i32_e32 vcc, 40, v68
	s_nop 1
	v_cndmask_b32_e32 v81, v214, v57, vcc
	v_cmp_lt_i32_e32 vcc, 41, v68
	v_max3_f32 v3, v3, v80, v81
	s_nop 0
	v_cndmask_b32_e32 v78, v214, v58, vcc
	v_cmp_lt_i32_e32 vcc, 42, v68
	s_nop 1
	v_cndmask_b32_e32 v79, v214, v59, vcc
	v_cmp_lt_i32_e32 vcc, 47, v68
	v_max3_f32 v3, v3, v78, v79
	s_nop 0
	v_cndmask_b32_e32 v76, v214, v60, vcc
	v_cmp_lt_i32_e32 vcc, 48, v68
	s_nop 1
	v_cndmask_b32_e32 v77, v214, v61, vcc
	v_cmp_lt_i32_e32 vcc, 49, v68
	v_max3_f32 v3, v3, v76, v77
	s_nop 0
	v_cndmask_b32_e32 v74, v214, v62, vcc
	v_cmp_lt_i32_e32 vcc, 50, v68
	s_nop 1
	v_cndmask_b32_e32 v75, v214, v63, vcc
	v_cmp_lt_i32_e32 vcc, 55, v68
	v_max3_f32 v3, v3, v74, v75
	s_nop 0
	v_cndmask_b32_e32 v70, v214, v64, vcc
	v_cmp_lt_i32_e32 vcc, 56, v68
	s_nop 1
	v_cndmask_b32_e32 v71, v214, v65, vcc
	v_cmp_lt_i32_e32 vcc, 57, v68
	v_max3_f32 v3, v3, v70, v71
	s_nop 0
	v_cndmask_b32_e32 v72, v214, v66, vcc
	v_cmp_lt_i32_e32 vcc, 58, v68
	s_nop 1
	v_cndmask_b32_e32 v73, v214, v67, vcc
	v_max3_f32 v3, v3, v72, v73
	s_nop 3
	s_waitcnt lgkmcnt(0)
	v_mov_b32_e32 v36, v3
	s_nop 1
	v_permlane32_swap_b32_e32 v36, v3
	v_max_f32_e32 v36, v36, v36
	v_max_f32_e32 v3, v3, v36
	v_max3_f32 v132, v218, v3, s46
	v_sub_f32_e32 v3, v218, v132
	v_exp_f32_e32 v68, v3
	s_nop 2
	v_cmp_eq_f32_e32 vcc, 1.0, v68
	s_cmp_eq_u64 vcc, exec
	s_nop 8
	s_cbranch_scc1 .LBB0_1449
	v_mul_f32_e32 v34, v34, v68
	v_mul_f32_e32 v35, v35, v68
	v_mul_f32_e32 v32, v32, v68
	v_mul_f32_e32 v33, v33, v68
	v_mul_f32_e32 v30, v30, v68
	v_mul_f32_e32 v31, v31, v68
	v_mul_f32_e32 v28, v28, v68
	v_mul_f32_e32 v29, v29, v68
	v_mul_f32_e32 v26, v26, v68
	v_mul_f32_e32 v27, v27, v68
	v_mul_f32_e32 v24, v24, v68
	v_mul_f32_e32 v25, v25, v68
	v_mul_f32_e32 v22, v22, v68
	v_mul_f32_e32 v23, v23, v68
	v_mul_f32_e32 v20, v20, v68
	v_mul_f32_e32 v21, v21, v68
	v_mul_f32_e32 v18, v18, v68
	v_mul_f32_e32 v19, v19, v68
	v_mul_f32_e32 v16, v16, v68
	v_mul_f32_e32 v17, v17, v68
	v_mul_f32_e32 v14, v14, v68
	v_mul_f32_e32 v15, v15, v68
	v_mul_f32_e32 v12, v12, v68
	v_mul_f32_e32 v13, v13, v68
	v_mul_f32_e32 v10, v10, v68
	v_mul_f32_e32 v11, v11, v68
	v_mul_f32_e32 v8, v8, v68
	v_mul_f32_e32 v9, v9, v68
	v_mul_f32_e32 v6, v6, v68
	v_mul_f32_e32 v7, v7, v68
	v_mul_f32_e32 v4, v4, v68
	v_mul_f32_e32 v5, v5, v68
.LBB0_1449:
	v_sub_f32_e32 v94, v94, v132
	v_sub_f32_e32 v95, v95, v132
	v_lshl_add_u32 v3, v136, 1, s38
	v_exp_f32_e32 v230, v94
	v_exp_f32_e32 v231, v95
	v_sub_f32_e32 v94, v98, v132
	v_sub_f32_e32 v95, v99, v132
	v_sub_f32_e32 v86, v86, v132
	v_sub_f32_e32 v87, v87, v132
	v_exp_f32_e32 v98, v94
	v_exp_f32_e32 v99, v95
	v_sub_f32_e32 v94, v96, v132
	v_sub_f32_e32 v95, v97, v132
	v_exp_f32_e32 v86, v86
	v_exp_f32_e32 v232, v94
	v_add_u32_e32 v94, v3, v190
	v_add_u32_e32 v186, 0x6800, v94
	v_exp_f32_e32 v233, v95
	ds_read2_b64 v[94:97], v186 offset0:64 offset1:66
	v_add_u32_e32 v3, v3, v191
	v_add_u32_e32 v3, 0x6800, v3
	ds_read2_b64 v[226:229], v3 offset0:64 offset1:66
	v_exp_f32_e32 v87, v87
	v_sub_f32_e32 v90, v90, v132
	v_sub_f32_e32 v91, v91, v132
	v_cvt_pk_bf16_f32 v223, v230, v231
	v_exp_f32_e32 v234, v90
	v_exp_f32_e32 v235, v91
	v_sub_f32_e32 v90, v92, v132
	v_sub_f32_e32 v91, v93, v132
	v_cvt_pk_bf16_f32 v222, v86, v87
	v_cvt_pk_bf16_f32 v224, v98, v99
	v_cvt_pk_bf16_f32 v225, v232, v233
	v_exp_f32_e32 v236, v90
	v_exp_f32_e32 v237, v91
	ds_read2_b64 v[90:93], v186 offset0:68 offset1:70
	s_waitcnt lgkmcnt(2)
	v_mfma_f32_32x32x16_bf16 v[20:35], v[94:97], v[222:225], v[20:35]
	v_add_f32_e64 v170, v170, -v132
	v_add_f32_e64 v171, v171, -v132
	v_add_f32_e64 v88, v88, -v132
	v_add_f32_e64 v89, v89, -v132
	v_exp_f32_e32 v170, v170
	v_exp_f32_e32 v171, v171
	v_cvt_pk_bf16_f32 v95, v234, v235
	v_cvt_pk_bf16_f32 v96, v236, v237
	v_cvt_pk_bf16_f32 v94, v170, v171
	s_waitcnt lgkmcnt(1)
	v_mfma_f32_32x32x16_bf16 v[4:19], v[226:229], v[222:225], v[4:19]
	v_exp_f32_e32 v222, v88
	v_exp_f32_e32 v223, v89
	s_nop 0
	v_cvt_pk_bf16_f32 v97, v222, v223
	s_waitcnt lgkmcnt(0)
	s_nop 0
	v_mfma_f32_32x32x16_bf16 v[20:35], v[90:93], v[94:97], v[20:35]
	ds_read2_b64 v[88:91], v3 offset0:68 offset1:70
	s_waitcnt lgkmcnt(0)
	v_mfma_f32_32x32x16_bf16 v[4:19], v[88:91], v[94:97], v[4:19]
	v_add_f32_e64 v80, v80, -v132
	v_add_f32_e64 v81, v81, -v132
	v_add_f32_e64 v78, v78, -v132
	v_add_f32_e64 v79, v79, -v132
	v_exp_f32_e32 v94, v80
	v_exp_f32_e32 v95, v81
	v_exp_f32_e32 v96, v78
	v_exp_f32_e32 v97, v79
	v_sub_f32_e32 v80, v76, v132
	v_sub_f32_e32 v81, v77, v132
	ds_read2_b64 v[76:79], v186 offset0:72 offset1:74
	v_sub_f32_e32 v84, v84, v132
	v_sub_f32_e32 v85, v85, v132
	v_sub_f32_e32 v82, v82, v132
	v_sub_f32_e32 v83, v83, v132
	ds_read2_b64 v[88:91], v3 offset0:72 offset1:74
	v_exp_f32_e32 v84, v84
	v_exp_f32_e32 v85, v85
	v_exp_f32_e32 v92, v82
	v_exp_f32_e32 v93, v83
	v_sub_f32_e32 v74, v74, v132
	v_sub_f32_e32 v75, v75, v132
	v_sub_f32_e32 v70, v70, v132
	v_sub_f32_e32 v71, v71, v132
	v_exp_f32_e32 v224, v80
	v_exp_f32_e32 v225, v81
	v_cvt_pk_bf16_f32 v80, v84, v85
	v_cvt_pk_bf16_f32 v81, v92, v93
	v_cvt_pk_bf16_f32 v82, v94, v95
	v_cvt_pk_bf16_f32 v83, v96, v97
	v_exp_f32_e32 v226, v74
	v_exp_f32_e32 v227, v75
	v_exp_f32_e32 v228, v70
	v_exp_f32_e32 v229, v71
	v_sub_f32_e32 v74, v72, v132
	v_sub_f32_e32 v75, v73, v132
	ds_read2_b64 v[70:73], v186 offset0:76 offset1:78
	s_waitcnt lgkmcnt(2)
	v_mfma_f32_32x32x16_bf16 v[20:35], v[76:79], v[80:83], v[20:35]
	v_cvt_pk_bf16_f32 v78, v224, v225
	v_cvt_pk_bf16_f32 v79, v226, v227
	s_mov_b64 s[24:25], 0
	s_waitcnt lgkmcnt(1)
	v_mfma_f32_32x32x16_bf16 v[4:19], v[88:91], v[80:83], v[4:19]
	v_exp_f32_e32 v82, v74
	v_exp_f32_e32 v83, v75
	v_cvt_pk_bf16_f32 v80, v228, v229
	ds_read2_b64 v[74:77], v3 offset0:76 offset1:78
	v_cvt_pk_bf16_f32 v81, v82, v83
	s_waitcnt lgkmcnt(1)
	s_nop 0
	v_mfma_f32_32x32x16_bf16 v[20:35], v[70:73], v[78:81], v[20:35]
	v_add_f32_e64 v70, v86, 0
	v_add_f32_e64 v71, v87, 0
	v_add_f32_e64 v70, v230, v70
	v_add_f32_e64 v71, v231, v71
	v_add_f32_e64 v70, v98, v70
	v_add_f32_e64 v71, v99, v71
	v_add_f32_e32 v70, v232, v70
	v_add_f32_e32 v71, v233, v71
	s_waitcnt lgkmcnt(0)
	v_mfma_f32_32x32x16_bf16 v[4:19], v[74:77], v[78:81], v[4:19]
	v_add_f32_e64 v70, v170, v70
	v_add_f32_e64 v71, v171, v71
	v_add_f32_e64 v70, v234, v70
	v_add_f32_e64 v71, v235, v71
	v_add_f32_e64 v70, v236, v70
	v_add_f32_e64 v71, v237, v71
	v_add_f32_e32 v70, v222, v70
	v_add_f32_e32 v71, v223, v71
	s_nop 0
	v_add_f32_e32 v70, v84, v70
	v_add_f32_e32 v71, v85, v71
	s_nop 0
	v_add_f32_e32 v70, v92, v70
	v_add_f32_e32 v71, v93, v71
	s_nop 0
	v_add_f32_e32 v70, v94, v70
	v_add_f32_e32 v71, v95, v71
	s_nop 0
	v_add_f32_e32 v70, v96, v70
	v_add_f32_e32 v71, v97, v71
	s_nop 0
	v_add_f32_e32 v70, v224, v70
	v_add_f32_e32 v71, v225, v71
	s_nop 0
	v_add_f32_e32 v70, v226, v70
	v_add_f32_e32 v71, v227, v71
	s_nop 0
	v_add_f32_e32 v70, v228, v70
	v_add_f32_e32 v71, v229, v71
	s_nop 0
	v_add_f32_e32 v70, v82, v70
	v_add_f32_e32 v71, v83, v71
	s_nop 0
	v_add_f32_e32 v3, v70, v71
	s_waitcnt lgkmcnt(0)
	v_mov_b32_e32 v70, v3
	s_nop 1
	v_permlane32_swap_b32_e32 v70, v3
	v_add_f32_e32 v3, v3, v70
	v_fmac_f32_e32 v3, v217, v68
.LBB0_1450:
	s_and_b64 vcc, exec, s[24:25]
	s_cbranch_vccz .LBB0_1463
	v_mov_b32_e32 v3, v157
	s_nop 0
	v_mul_f32_e64 v36, v69, -v3
	v_cndmask_b32_e64 v44, v214, v36, s[0:1]
	v_mov_b32_e32 v46, v3
	v_fma_f32 v36, 0, v3, v44
	v_add_f32_e32 v84, v2, v36
	v_add_f32_e32 v85, v3, v36
	v_fma_f32 v86, v46, s64, v36
	v_fma_f32 v87, v46, s65, v36
	ds_read_b128 v[36:39], v220 offset:17920
	v_fmamk_f32 v40, v3, 0x41000000, v44
	v_add_f32_e32 v88, v2, v40
	v_add_f32_e32 v89, v3, v40
	v_fma_f32 v90, v46, s64, v40
	v_fma_f32 v91, v46, s65, v40
	v_fmamk_f32 v40, v3, 0x41800000, v44
	v_add_f32_e32 v92, v2, v40
	v_add_f32_e32 v93, v3, v40
	v_fma_f32 v94, v46, s64, v40
	v_fma_f32 v95, v46, s65, v40
	v_fmamk_f32 v40, v3, 0x41c00000, v44
	v_add_f32_e32 v96, v2, v40
	v_add_f32_e32 v97, v3, v40
	v_fma_f32 v98, v46, s64, v40
	v_fma_f32 v99, v46, s65, v40
	ds_read_b128 v[40:43], v220 offset:17952
	v_fmamk_f32 v48, v3, 0x42000000, v44
	s_waitcnt lgkmcnt(1)
	v_mfma_f32_32x32x16_bf16 v[84:99], v[36:39], v[100:103], v[84:99]
	v_fmamk_f32 v50, v3, 0x42200000, v44
	v_fmamk_f32 v52, v3, 0x42400000, v44
	v_fmac_f32_e32 v44, 0x42600000, v3
	v_add_f32_e64 v68, v2, v48
	v_add_f32_e64 v69, v3, v48
	v_fma_f32 v70, v46, s64, v48
	v_fma_f32 v71, v46, s65, v48
	v_add_f32_e32 v72, v2, v50
	v_add_f32_e32 v73, v3, v50
	v_fma_f32 v74, v46, s64, v50
	v_fma_f32 v75, v46, s65, v50
	s_waitcnt lgkmcnt(0)
	v_mfma_f32_32x32x16_bf16 v[84:99], v[40:43], v[104:107], v[84:99]
	ds_read_b128 v[36:39], v220 offset:17984
	ds_read_b128 v[40:43], v220 offset:18016
	v_add_f32_e64 v76, v2, v52
	v_add_f32_e64 v77, v3, v52
	v_fma_f32 v78, v46, s64, v52
	v_fma_f32 v79, v46, s65, v52
	v_add_f32_e32 v80, v2, v44
	v_add_f32_e32 v81, v3, v44
	v_fma_f32 v82, v46, s64, v44
	v_fma_f32 v83, v46, s65, v44
	s_nop 1
	s_waitcnt lgkmcnt(1)
	v_mfma_f32_32x32x16_bf16 v[84:99], v[36:39], v[108:111], v[84:99]
	ds_read_b128 v[36:39], v219 offset:17920
	s_nop 5
	s_waitcnt lgkmcnt(1)
	v_mfma_f32_32x32x16_bf16 v[84:99], v[40:43], v[112:115], v[84:99]
	ds_read_b128 v[40:43], v219 offset:17952
	s_waitcnt lgkmcnt(1)
	v_mfma_f32_32x32x16_bf16 v[68:83], v[36:39], v[100:103], v[68:83]
	s_nop 8
	v_max3_f32 v3, v84, s97, v85
	v_max3_f32 v3, v3, v86, v87
	v_max3_f32 v3, v3, v88, v89
	v_max3_f32 v3, v3, v90, v91
	v_max3_f32 v3, v3, v92, v93
	v_max3_f32 v3, v3, v94, v95
	v_max3_f32 v3, v3, v96, v97
	s_waitcnt lgkmcnt(0)
	v_mfma_f32_32x32x16_bf16 v[68:83], v[40:43], v[104:107], v[68:83]
	ds_read_b128 v[36:39], v219 offset:17984
	ds_read_b128 v[40:43], v219 offset:18016
	v_max3_f32 v3, v3, v98, v99
	s_waitcnt lgkmcnt(1)
	v_mfma_f32_32x32x16_bf16 v[68:83], v[36:39], v[108:111], v[68:83]
	s_waitcnt lgkmcnt(0)
	v_mfma_f32_32x32x16_bf16 v[68:83], v[40:43], v[112:115], v[68:83]
	s_nop 11
	v_max3_f32 v3, v3, v68, v69
	v_max3_f32 v3, v3, v70, v71
	v_max3_f32 v3, v3, v72, v73
	v_max3_f32 v3, v3, v74, v75
	v_max3_f32 v3, v3, v76, v77
	v_max3_f32 v3, v3, v78, v79
	v_max3_f32 v3, v3, v80, v81
	v_max3_f32 v3, v3, v82, v83
	s_waitcnt lgkmcnt(0)
	v_mov_b32_e32 v36, v3
	s_nop 1
	v_permlane32_swap_b32_e32 v36, v3
	v_max_f32_e32 v36, v36, v36
	v_max_f32_e32 v3, v3, v36
	v_max3_f32 v132, v218, v3, s46
	v_sub_f32_e32 v3, v218, v132
	v_exp_f32_e32 v170, v3
	s_nop 2
	v_cmp_eq_f32_e32 vcc, 1.0, v170
	s_cmp_eq_u64 vcc, exec
	s_nop 4
	s_cbranch_scc1 .LBB0_1453
	v_mul_f32_e32 v34, v34, v170
	v_mul_f32_e32 v35, v35, v170
	v_mul_f32_e32 v32, v32, v170
	v_mul_f32_e32 v33, v33, v170
	v_mul_f32_e32 v30, v30, v170
	v_mul_f32_e32 v31, v31, v170
	v_mul_f32_e32 v28, v28, v170
	v_mul_f32_e32 v29, v29, v170
	v_mul_f32_e32 v26, v26, v170
	v_mul_f32_e32 v27, v27, v170
	v_mul_f32_e32 v24, v24, v170
	v_mul_f32_e32 v25, v25, v170
	v_mul_f32_e32 v22, v22, v170
	v_mul_f32_e32 v23, v23, v170
	v_mul_f32_e32 v20, v20, v170
	v_mul_f32_e32 v21, v21, v170
	v_mul_f32_e32 v18, v18, v170
	v_mul_f32_e32 v19, v19, v170
	v_mul_f32_e32 v16, v16, v170
	v_mul_f32_e32 v17, v17, v170
	v_mul_f32_e32 v14, v14, v170
	v_mul_f32_e32 v15, v15, v170
	v_mul_f32_e32 v12, v12, v170
	v_mul_f32_e32 v13, v13, v170
	v_mul_f32_e32 v10, v10, v170
	v_mul_f32_e32 v11, v11, v170
	v_mul_f32_e32 v8, v8, v170
	v_mul_f32_e32 v9, v9, v170
	v_mul_f32_e32 v6, v6, v170
	v_mul_f32_e32 v7, v7, v170
	v_mul_f32_e32 v4, v4, v170
	v_mul_f32_e32 v5, v5, v170
.LBB0_1453:
	v_add_u32_e32 v3, v165, v196
	v_sub_f32_e32 v84, v84, v132
	v_sub_f32_e32 v85, v85, v132
	v_sub_f32_e32 v86, v86, v132
	v_sub_f32_e32 v87, v87, v132
	v_sub_f32_e32 v88, v88, v132
	v_sub_f32_e32 v89, v89, v132
	v_sub_f32_e32 v90, v90, v132
	v_sub_f32_e32 v91, v91, v132
	v_add_u32_e32 v171, v3, v190
	v_exp_f32_e32 v84, v84
	v_exp_f32_e32 v85, v85
	v_exp_f32_e32 v86, v86
	v_exp_f32_e32 v87, v87
	v_exp_f32_e32 v88, v88
	v_exp_f32_e32 v89, v89
	v_exp_f32_e32 v90, v90
	v_exp_f32_e32 v91, v91
	v_add_u32_e32 v171, 0x6800, v171
	ds_read2_b64 v[226:229], v171 offset0:64 offset1:66
	ds_read2_b64 v[230:233], v171 offset0:68 offset1:70
	v_add_u32_e32 v3, v3, v191
	v_cvt_pk_bf16_f32 v222, v84, v85
	v_cvt_pk_bf16_f32 v223, v86, v87
	v_cvt_pk_bf16_f32 v224, v88, v89
	v_cvt_pk_bf16_f32 v225, v90, v91
	v_add_u32_e32 v3, 0x6800, v3
	v_sub_f32_e32 v92, v92, v132
	v_sub_f32_e32 v93, v93, v132
	s_waitcnt lgkmcnt(1)
	v_mfma_f32_32x32x16_bf16 v[20:35], v[226:229], v[222:225], v[20:35]
	ds_read2_b64 v[226:229], v3 offset0:64 offset1:66
	ds_read2_b64 v[234:237], v3 offset0:68 offset1:70
	v_add_f32_e64 v94, v94, -v132
	v_add_f32_e64 v95, v95, -v132
	v_add_f32_e64 v96, v96, -v132
	v_add_f32_e64 v97, v97, -v132
	v_sub_f32_e32 v98, v98, v132
	v_sub_f32_e32 v99, v99, v132
	v_exp_f32_e32 v92, v92
	v_exp_f32_e32 v93, v93
	v_exp_f32_e32 v94, v94
	s_waitcnt lgkmcnt(1)
	v_mfma_f32_32x32x16_bf16 v[4:19], v[226:229], v[222:225], v[4:19]
	v_exp_f32_e32 v95, v95
	v_exp_f32_e32 v96, v96
	v_exp_f32_e32 v97, v97
	v_exp_f32_e32 v98, v98
	v_exp_f32_e32 v99, v99
	v_cvt_pk_bf16_f32 v222, v92, v93
	v_cvt_pk_bf16_f32 v223, v94, v95
	v_cvt_pk_bf16_f32 v224, v96, v97
	v_cvt_pk_bf16_f32 v225, v98, v99
	s_nop 1
	v_mfma_f32_32x32x16_bf16 v[20:35], v[230:233], v[222:225], v[20:35]
	s_waitcnt lgkmcnt(0)
	v_mfma_f32_32x32x16_bf16 v[4:19], v[234:237], v[222:225], v[4:19]
	v_add_f32_e64 v74, v74, -v132
	v_add_f32_e64 v75, v75, -v132
	v_add_f32_e64 v68, v68, -v132
	v_add_f32_e64 v69, v69, -v132
	v_add_f32_e64 v70, v70, -v132
	v_add_f32_e64 v71, v71, -v132
	v_sub_f32_e32 v72, v72, v132
	v_sub_f32_e32 v73, v73, v132
	v_exp_f32_e32 v230, v74
	v_exp_f32_e32 v231, v75
	v_sub_f32_e32 v74, v76, v132
	v_sub_f32_e32 v75, v77, v132
	v_exp_f32_e32 v68, v68
	v_exp_f32_e32 v69, v69
	v_exp_f32_e32 v70, v70
	v_exp_f32_e32 v71, v71
	v_exp_f32_e32 v72, v72
	v_exp_f32_e32 v73, v73
	v_exp_f32_e32 v232, v74
	v_exp_f32_e32 v233, v75
	v_sub_f32_e32 v74, v78, v132
	v_sub_f32_e32 v75, v79, v132
	v_cvt_pk_bf16_f32 v76, v72, v73
	v_exp_f32_e32 v234, v74
	v_exp_f32_e32 v235, v75
	v_sub_f32_e32 v74, v80, v132
	v_sub_f32_e32 v75, v81, v132
	ds_read2_b64 v[78:81], v171 offset0:72 offset1:74
	ds_read2_b64 v[222:225], v171 offset0:76 offset1:78
	v_exp_f32_e32 v236, v74
	v_exp_f32_e32 v237, v75
	v_sub_f32_e32 v74, v82, v132
	v_sub_f32_e32 v75, v83, v132
	v_cvt_pk_bf16_f32 v77, v230, v231
	v_exp_f32_e32 v82, v74
	v_exp_f32_e32 v83, v75
	v_cvt_pk_bf16_f32 v74, v68, v69
	v_cvt_pk_bf16_f32 v75, v70, v71
	s_mov_b64 s[24:25], 0
	s_waitcnt lgkmcnt(1)
	v_mfma_f32_32x32x16_bf16 v[20:35], v[78:81], v[74:77], v[20:35]
	ds_read2_b64 v[78:81], v3 offset0:72 offset1:74
	ds_read2_b64 v[226:229], v3 offset0:76 offset1:78
	s_waitcnt lgkmcnt(1)
	v_mfma_f32_32x32x16_bf16 v[4:19], v[78:81], v[74:77], v[4:19]
	v_cvt_pk_bf16_f32 v74, v232, v233
	v_cvt_pk_bf16_f32 v75, v234, v235
	v_cvt_pk_bf16_f32 v76, v236, v237
	v_cvt_pk_bf16_f32 v77, v82, v83
	s_nop 1
	v_mfma_f32_32x32x16_bf16 v[20:35], v[222:225], v[74:77], v[20:35]
	s_waitcnt lgkmcnt(0)
	v_mfma_f32_32x32x16_bf16 v[4:19], v[226:229], v[74:77], v[4:19]
	v_add_f32_e64 v74, v84, 0
	v_add_f32_e64 v75, v85, 0
	v_add_f32_e64 v74, v86, v74
	v_add_f32_e64 v75, v87, v75
	v_add_f32_e64 v74, v88, v74
	v_add_f32_e64 v75, v89, v75
	v_add_f32_e32 v74, v90, v74
	v_add_f32_e32 v75, v91, v75
	s_nop 0
	v_add_f32_e32 v74, v92, v74
	v_add_f32_e32 v75, v93, v75
	s_nop 0
	v_add_f32_e32 v74, v94, v74
	v_add_f32_e32 v75, v95, v75
	s_nop 0
	v_add_f32_e32 v74, v96, v74
	v_add_f32_e32 v75, v97, v75
	s_nop 0
	v_add_f32_e32 v74, v98, v74
	v_add_f32_e32 v75, v99, v75
	s_nop 0
	v_add_f32_e32 v68, v68, v74
	v_add_f32_e32 v69, v69, v75
	s_nop 0
	v_add_f32_e32 v68, v70, v68
	v_add_f32_e32 v69, v71, v69
	s_nop 0
	v_add_f32_e32 v68, v72, v68
	v_add_f32_e32 v69, v73, v69
	s_nop 0
	v_add_f32_e32 v68, v230, v68
	v_add_f32_e32 v69, v231, v69
	s_nop 0
	v_add_f32_e32 v68, v232, v68
	v_add_f32_e32 v69, v233, v69
	s_nop 0
	v_add_f32_e32 v68, v234, v68
	v_add_f32_e32 v69, v235, v69
	s_nop 0
	v_add_f32_e32 v68, v236, v68
	v_add_f32_e32 v69, v237, v69
	s_nop 0
	v_add_f32_e32 v68, v82, v68
	v_add_f32_e32 v69, v83, v69
	s_nop 0
	v_add_f32_e32 v3, v68, v69
	s_waitcnt lgkmcnt(0)
	v_mov_b32_e32 v68, v3
	s_nop 1
	v_permlane32_swap_b32_e32 v68, v3
	v_add_f32_e32 v3, v3, v68
	v_fmac_f32_e32 v3, v217, v170

.LBB0_1455:
	v_sub_u32_e32 v68, v161, v221
	s_cmp_gt_i32 s39, s76
	v_cvt_f32_i32_e32 v69, v68
	s_cselect_b64 s[0:1], -1, 0
	s_and_b64 s[0:1], s[2:3], s[0:1]
	s_andn2_b64 vcc, exec, s[0:1]
	s_mov_b64 s[0:1], -1
	s_cbranch_vccz .LBB0_1459
	v_mov_b32_e32 v3, v157
	ds_read_b128 v[52:55], v220 offset:17920
	ds_read_b128 v[56:59], v220 offset:17952
	v_mul_f32_e64 v66, v69, -v3
	v_mov_b32_e32 v78, v3
	v_fma_f32 v38, 0, v3, v66
	v_fmamk_f32 v42, v3, 0x41000000, v66
	v_fmamk_f32 v46, v3, 0x41800000, v66
	v_fmamk_f32 v50, v3, 0x41c00000, v66
	v_add_f32_e32 v36, v2, v38
	v_add_f32_e32 v37, v3, v38
	v_fma_f32 v39, v78, s65, v38
	v_fma_f32 v38, v78, s64, v38
	v_add_f32_e32 v40, v2, v42
	v_add_f32_e32 v41, v3, v42
	v_fma_f32 v43, v78, s65, v42
	v_fma_f32 v42, v78, s64, v42
	v_add_f32_e32 v44, v2, v46
	v_add_f32_e32 v45, v3, v46
	v_fma_f32 v47, v78, s65, v46
	v_fma_f32 v46, v78, s64, v46
	v_add_f32_e32 v48, v2, v50
	v_add_f32_e32 v49, v3, v50
	v_fma_f32 v51, v78, s65, v50
	v_fma_f32 v50, v78, s64, v50
	v_fmamk_f32 v60, v3, 0x42200000, v66
	v_fmamk_f32 v62, v3, 0x42400000, v66
	s_waitcnt lgkmcnt(1)
	v_mfma_f32_32x32x16_bf16 v[36:51], v[52:55], v[100:103], v[36:51]
	v_cmp_gt_u32_e32 vcc, s47, v68
	s_waitcnt lgkmcnt(0)
	v_mfma_f32_32x32x16_bf16 v[36:51], v[56:59], v[104:107], v[36:51]
	ds_read_b128 v[52:55], v220 offset:17984
	ds_read_b128 v[56:59], v220 offset:18016
	ds_read_b128 v[70:73], v219 offset:17920
	ds_read_b128 v[74:77], v219 offset:17952
	s_waitcnt lgkmcnt(3)
	v_mfma_f32_32x32x16_bf16 v[36:51], v[52:55], v[108:111], v[36:51]
	v_fmamk_f32 v54, v3, 0x42000000, v66
	v_fmac_f32_e32 v66, 0x42600000, v3
	v_add_f32_e64 v52, v2, v54
	v_add_f32_e64 v53, v3, v54
	v_fma_f32 v55, v78, s65, v54
	v_fma_f32 v54, v78, s64, v54
	v_add_f32_e32 v64, v2, v66
	v_add_f32_e32 v65, v3, v66
	v_fma_f32 v67, v78, s65, v66
	v_fma_f32 v66, v78, s64, v66
	s_waitcnt lgkmcnt(2)
	v_mfma_f32_32x32x16_bf16 v[36:51], v[56:59], v[112:115], v[36:51]
	v_add_f32_e64 v56, v2, v60
	v_add_f32_e64 v57, v3, v60
	v_fma_f32 v58, v78, s64, v60
	v_fma_f32 v59, v78, s65, v60
	v_add_f32_e64 v60, v2, v62
	v_add_f32_e64 v61, v3, v62
	v_fma_f32 v63, v78, s65, v62
	v_fma_f32 v62, v78, s64, v62
	v_add_u32_e32 v3, -1, v68
	s_nop 3
	v_cndmask_b32_e32 v88, v214, v36, vcc
	s_waitcnt lgkmcnt(1)
	v_mfma_f32_32x32x16_bf16 v[52:67], v[70:73], v[100:103], v[52:67]
	ds_read_b128 v[70:73], v219 offset:17984
	ds_read_b128 v[78:81], v219 offset:18016
	v_cmp_gt_u32_e32 vcc, s47, v3
	v_add_u32_e32 v36, -2, v68
	s_nop 0
	v_cndmask_b32_e32 v89, v214, v37, vcc
	v_cmp_gt_u32_e32 vcc, s47, v36
	v_add_u32_e32 v36, -3, v68
	s_waitcnt lgkmcnt(2)
	v_mfma_f32_32x32x16_bf16 v[52:67], v[74:77], v[104:107], v[52:67]
	v_cndmask_b32_e32 v94, v214, v38, vcc
	v_cmp_gt_u32_e32 vcc, s47, v36
	v_add_u32_e32 v36, -8, v68
	v_max3_f32 v3, v88, s97, v89
	v_cndmask_b32_e32 v95, v214, v39, vcc
	v_cmp_gt_u32_e32 vcc, s47, v36
	v_add_u32_e32 v36, -9, v68
	s_waitcnt lgkmcnt(1)
	v_mfma_f32_32x32x16_bf16 v[52:67], v[70:73], v[108:111], v[52:67]
	v_cndmask_b32_e32 v96, v214, v40, vcc
	v_cmp_gt_u32_e32 vcc, s47, v36
	v_add_u32_e32 v36, -10, v68
	v_max3_f32 v3, v3, v94, v95
	v_cndmask_b32_e32 v97, v214, v41, vcc
	v_cmp_gt_u32_e32 vcc, s47, v36
	v_add_u32_e32 v36, -11, v68
	s_waitcnt lgkmcnt(0)
	v_mfma_f32_32x32x16_bf16 v[52:67], v[78:81], v[112:115], v[52:67]
	v_cndmask_b32_e32 v98, v214, v42, vcc
	v_cmp_gt_u32_e32 vcc, s47, v36
	v_add_u32_e32 v36, -16, v68
	v_max3_f32 v3, v3, v96, v97
	v_cndmask_b32_e32 v99, v214, v43, vcc
	v_cmp_gt_u32_e32 vcc, s47, v36
	v_subrev_u32_e32 v36, 17, v68
	v_max3_f32 v3, v3, v98, v99
	v_cndmask_b32_e32 v170, v214, v44, vcc
	v_cmp_gt_u32_e32 vcc, s47, v36
	v_subrev_u32_e32 v36, 18, v68
	s_nop 0
	v_cndmask_b32_e32 v171, v214, v45, vcc
	v_cmp_gt_u32_e32 vcc, s47, v36
	v_subrev_u32_e32 v36, 19, v68
	v_max3_f32 v3, v3, v170, v171
	v_cndmask_b32_e32 v90, v214, v46, vcc
	v_cmp_gt_u32_e32 vcc, s47, v36
	v_subrev_u32_e32 v36, 24, v68
	s_nop 0
	v_cndmask_b32_e32 v91, v214, v47, vcc
	v_cmp_gt_u32_e32 vcc, s47, v36
	v_subrev_u32_e32 v36, 25, v68
	v_max3_f32 v3, v3, v90, v91
	v_cndmask_b32_e32 v92, v214, v48, vcc
	v_cmp_gt_u32_e32 vcc, s47, v36
	v_subrev_u32_e32 v36, 26, v68
	s_nop 0
	v_cndmask_b32_e32 v93, v214, v49, vcc
	v_cmp_gt_u32_e32 vcc, s47, v36
	v_subrev_u32_e32 v36, 27, v68
	v_max3_f32 v3, v3, v92, v93
	v_cndmask_b32_e32 v86, v214, v50, vcc
	v_cmp_gt_u32_e32 vcc, s47, v36
	v_subrev_u32_e32 v36, 32, v68
	s_nop 0
	v_cndmask_b32_e32 v87, v214, v51, vcc
	v_cmp_gt_u32_e32 vcc, s47, v36
	v_subrev_u32_e32 v36, 33, v68
	v_max3_f32 v3, v3, v86, v87
	v_cndmask_b32_e32 v76, v214, v52, vcc
	v_cmp_gt_u32_e32 vcc, s47, v36
	v_subrev_u32_e32 v36, 34, v68
	s_nop 0
	v_cndmask_b32_e32 v77, v214, v53, vcc
	v_cmp_gt_u32_e32 vcc, s47, v36
	v_subrev_u32_e32 v36, 35, v68
	v_max3_f32 v3, v3, v76, v77
	v_cndmask_b32_e32 v78, v214, v54, vcc
	v_cmp_gt_u32_e32 vcc, s47, v36
	v_subrev_u32_e32 v36, 40, v68
	s_nop 0
	v_cndmask_b32_e32 v79, v214, v55, vcc
	v_cmp_gt_u32_e32 vcc, s47, v36
	v_subrev_u32_e32 v36, 41, v68
	v_max3_f32 v3, v3, v78, v79
	v_cndmask_b32_e32 v80, v214, v56, vcc
	v_cmp_gt_u32_e32 vcc, s47, v36
	v_subrev_u32_e32 v36, 42, v68
	s_nop 0
	v_cndmask_b32_e32 v81, v214, v57, vcc
	v_cmp_gt_u32_e32 vcc, s47, v36
	v_subrev_u32_e32 v36, 43, v68
	v_max3_f32 v3, v3, v80, v81
	v_cndmask_b32_e32 v82, v214, v58, vcc
	v_cmp_gt_u32_e32 vcc, s47, v36
	v_subrev_u32_e32 v36, 48, v68
	s_nop 0
	v_cndmask_b32_e32 v83, v214, v59, vcc
	v_cmp_gt_u32_e32 vcc, s47, v36
	v_subrev_u32_e32 v36, 49, v68
	v_max3_f32 v3, v3, v82, v83
	v_cndmask_b32_e32 v84, v214, v60, vcc
	v_cmp_gt_u32_e32 vcc, s47, v36
	v_subrev_u32_e32 v36, 50, v68
	s_nop 0
	v_cndmask_b32_e32 v85, v214, v61, vcc
	v_cmp_gt_u32_e32 vcc, s47, v36
	v_subrev_u32_e32 v36, 51, v68
	v_max3_f32 v3, v3, v84, v85
	v_cndmask_b32_e32 v74, v214, v62, vcc
	v_cmp_gt_u32_e32 vcc, s47, v36
	v_subrev_u32_e32 v36, 56, v68
	s_nop 0
	v_cndmask_b32_e32 v75, v214, v63, vcc
	v_cmp_gt_u32_e32 vcc, s47, v36
	v_subrev_u32_e32 v36, 57, v68
	v_max3_f32 v3, v3, v74, v75
	v_cndmask_b32_e32 v70, v214, v64, vcc
	v_cmp_gt_u32_e32 vcc, s47, v36
	v_subrev_u32_e32 v36, 58, v68
	s_nop 0
	v_cndmask_b32_e32 v71, v214, v65, vcc
	v_cmp_gt_u32_e32 vcc, s47, v36
	v_subrev_u32_e32 v36, 59, v68
	v_max3_f32 v3, v3, v70, v71
	v_cndmask_b32_e32 v72, v214, v66, vcc
	v_cmp_gt_u32_e32 vcc, s47, v36
	s_nop 1
	v_cndmask_b32_e32 v73, v214, v67, vcc
	v_max3_f32 v3, v3, v72, v73
	s_nop 3
	s_waitcnt lgkmcnt(0)
	v_mov_b32_e32 v36, v3
	s_nop 1
	v_permlane32_swap_b32_e32 v36, v3
	v_max_f32_e32 v36, v36, v36
	v_max_f32_e32 v3, v3, v36
	v_max3_f32 v132, v218, v3, s46
	v_sub_f32_e32 v3, v218, v132
	v_exp_f32_e32 v68, v3
	s_nop 2
	v_cmp_eq_f32_e32 vcc, 1.0, v68
	s_cmp_eq_u64 vcc, exec
	s_nop 8
	s_cbranch_scc1 .LBB0_1458
	v_mul_f32_e32 v34, v34, v68
	v_mul_f32_e32 v35, v35, v68
	v_mul_f32_e32 v32, v32, v68
	v_mul_f32_e32 v33, v33, v68
	v_mul_f32_e32 v30, v30, v68
	v_mul_f32_e32 v31, v31, v68
	v_mul_f32_e32 v28, v28, v68
	v_mul_f32_e32 v29, v29, v68
	v_mul_f32_e32 v26, v26, v68
	v_mul_f32_e32 v27, v27, v68
	v_mul_f32_e32 v24, v24, v68
	v_mul_f32_e32 v25, v25, v68
	v_mul_f32_e32 v22, v22, v68
	v_mul_f32_e32 v23, v23, v68
	v_mul_f32_e32 v20, v20, v68
	v_mul_f32_e32 v21, v21, v68
	v_mul_f32_e32 v18, v18, v68
	v_mul_f32_e32 v19, v19, v68
	v_mul_f32_e32 v16, v16, v68
	v_mul_f32_e32 v17, v17, v68
	v_mul_f32_e32 v14, v14, v68
	v_mul_f32_e32 v15, v15, v68
	v_mul_f32_e32 v12, v12, v68
	v_mul_f32_e32 v13, v13, v68
	v_mul_f32_e32 v10, v10, v68
	v_mul_f32_e32 v11, v11, v68
	v_mul_f32_e32 v8, v8, v68
	v_mul_f32_e32 v9, v9, v68
	v_mul_f32_e32 v6, v6, v68
	v_mul_f32_e32 v7, v7, v68
	v_mul_f32_e32 v4, v4, v68
	v_mul_f32_e32 v5, v5, v68
.LBB0_1458:
	v_sub_f32_e32 v94, v94, v132
	v_sub_f32_e32 v95, v95, v132
	v_lshl_add_u32 v3, v136, 1, s38
	v_exp_f32_e32 v230, v94
	v_exp_f32_e32 v231, v95
	v_sub_f32_e32 v94, v96, v132
	v_sub_f32_e32 v95, v97, v132
	v_sub_f32_e32 v88, v88, v132
	v_sub_f32_e32 v89, v89, v132
	v_exp_f32_e32 v232, v94
	v_exp_f32_e32 v233, v95
	v_sub_f32_e32 v94, v98, v132
	v_sub_f32_e32 v95, v99, v132
	v_exp_f32_e32 v88, v88
	v_exp_f32_e32 v98, v94
	v_add_u32_e32 v94, v3, v190
	v_add_u32_e32 v186, 0x6800, v94
	v_exp_f32_e32 v99, v95
	ds_read2_b64 v[94:97], v186 offset0:64 offset1:66
	v_add_u32_e32 v3, v3, v191
	v_add_u32_e32 v3, 0x6800, v3
	ds_read2_b64 v[226:229], v3 offset0:64 offset1:66
	v_exp_f32_e32 v89, v89
	v_sub_f32_e32 v90, v90, v132
	v_sub_f32_e32 v91, v91, v132
	v_cvt_pk_bf16_f32 v223, v230, v231
	v_exp_f32_e32 v234, v90
	v_exp_f32_e32 v235, v91
	v_sub_f32_e32 v90, v92, v132
	v_sub_f32_e32 v91, v93, v132
	v_cvt_pk_bf16_f32 v222, v88, v89
	v_cvt_pk_bf16_f32 v224, v232, v233
	v_cvt_pk_bf16_f32 v225, v98, v99
	v_exp_f32_e32 v236, v90
	v_exp_f32_e32 v237, v91
	ds_read2_b64 v[90:93], v186 offset0:68 offset1:70
	s_waitcnt lgkmcnt(2)
	v_mfma_f32_32x32x16_bf16 v[20:35], v[94:97], v[222:225], v[20:35]
	v_add_f32_e64 v170, v170, -v132
	v_add_f32_e64 v171, v171, -v132
	v_add_f32_e64 v86, v86, -v132
	v_add_f32_e64 v87, v87, -v132
	v_exp_f32_e32 v170, v170
	v_exp_f32_e32 v171, v171
	v_cvt_pk_bf16_f32 v95, v234, v235
	v_cvt_pk_bf16_f32 v96, v236, v237
	v_cvt_pk_bf16_f32 v94, v170, v171
	s_waitcnt lgkmcnt(1)
	v_mfma_f32_32x32x16_bf16 v[4:19], v[226:229], v[222:225], v[4:19]
	v_exp_f32_e32 v222, v86
	v_exp_f32_e32 v223, v87
	s_nop 0
	v_cvt_pk_bf16_f32 v97, v222, v223
	s_waitcnt lgkmcnt(0)
	s_nop 0
	v_mfma_f32_32x32x16_bf16 v[20:35], v[90:93], v[94:97], v[20:35]
	ds_read2_b64 v[90:93], v3 offset0:68 offset1:70
	s_waitcnt lgkmcnt(0)
	v_mfma_f32_32x32x16_bf16 v[4:19], v[90:93], v[94:97], v[4:19]
	v_add_f32_e64 v76, v76, -v132
	v_add_f32_e64 v77, v77, -v132
	v_add_f32_e64 v74, v74, -v132
	v_add_f32_e64 v75, v75, -v132
	v_exp_f32_e32 v90, v76
	v_exp_f32_e32 v91, v77
	v_sub_f32_e32 v76, v78, v132
	v_sub_f32_e32 v77, v79, v132
	v_sub_f32_e32 v70, v70, v132
	v_sub_f32_e32 v71, v71, v132
	v_exp_f32_e32 v92, v76
	v_exp_f32_e32 v93, v77
	v_sub_f32_e32 v76, v80, v132
	v_sub_f32_e32 v77, v81, v132
	v_sub_f32_e32 v80, v84, v132
	v_sub_f32_e32 v81, v85, v132
	v_exp_f32_e32 v94, v76
	v_exp_f32_e32 v95, v77
	v_sub_f32_e32 v76, v82, v132
	v_sub_f32_e32 v77, v83, v132
	ds_read2_b64 v[84:87], v3 offset0:72 offset1:74
	v_exp_f32_e32 v96, v76
	v_exp_f32_e32 v97, v77
	ds_read2_b64 v[76:79], v186 offset0:72 offset1:74
	v_exp_f32_e32 v224, v80
	v_exp_f32_e32 v225, v81
	v_cvt_pk_bf16_f32 v80, v90, v91
	v_cvt_pk_bf16_f32 v81, v92, v93
	v_cvt_pk_bf16_f32 v82, v94, v95
	v_cvt_pk_bf16_f32 v83, v96, v97
	v_exp_f32_e32 v226, v74
	v_exp_f32_e32 v227, v75
	v_exp_f32_e32 v228, v70
	v_exp_f32_e32 v229, v71
	v_sub_f32_e32 v74, v72, v132
	v_sub_f32_e32 v75, v73, v132
	ds_read2_b64 v[70:73], v186 offset0:76 offset1:78
	s_waitcnt lgkmcnt(1)
	v_mfma_f32_32x32x16_bf16 v[20:35], v[76:79], v[80:83], v[20:35]
	v_cvt_pk_bf16_f32 v78, v224, v225
	v_cvt_pk_bf16_f32 v79, v226, v227
	s_mov_b64 s[0:1], 0
	v_mfma_f32_32x32x16_bf16 v[4:19], v[84:87], v[80:83], v[4:19]
	v_exp_f32_e32 v82, v74
	v_exp_f32_e32 v83, v75
	v_cvt_pk_bf16_f32 v80, v228, v229
	ds_read2_b64 v[74:77], v3 offset0:76 offset1:78
	v_cvt_pk_bf16_f32 v81, v82, v83
	s_waitcnt lgkmcnt(1)
	s_nop 0
	v_mfma_f32_32x32x16_bf16 v[20:35], v[70:73], v[78:81], v[20:35]
	v_add_f32_e64 v70, v88, 0
	v_add_f32_e64 v71, v89, 0
	v_add_f32_e64 v70, v230, v70
	v_add_f32_e64 v71, v231, v71
	v_add_f32_e64 v70, v232, v70
	v_add_f32_e64 v71, v233, v71
	v_add_f32_e32 v70, v98, v70
	v_add_f32_e32 v71, v99, v71
	s_waitcnt lgkmcnt(0)
	v_mfma_f32_32x32x16_bf16 v[4:19], v[74:77], v[78:81], v[4:19]
	v_add_f32_e64 v70, v170, v70
	v_add_f32_e64 v71, v171, v71
	v_add_f32_e64 v70, v234, v70
	v_add_f32_e64 v71, v235, v71
	v_add_f32_e64 v70, v236, v70
	v_add_f32_e64 v71, v237, v71
	v_add_f32_e32 v70, v222, v70
	v_add_f32_e32 v71, v223, v71
	s_nop 0
	v_add_f32_e32 v70, v90, v70
	v_add_f32_e32 v71, v91, v71
	s_nop 0
	v_add_f32_e32 v70, v92, v70
	v_add_f32_e32 v71, v93, v71
	s_nop 0
	v_add_f32_e32 v70, v94, v70
	v_add_f32_e32 v71, v95, v71
	s_nop 0
	v_add_f32_e32 v70, v96, v70
	v_add_f32_e32 v71, v97, v71
	s_nop 0
	v_add_f32_e32 v70, v224, v70
	v_add_f32_e32 v71, v225, v71
	s_nop 0
	v_add_f32_e32 v70, v226, v70
	v_add_f32_e32 v71, v227, v71
	s_nop 0
	v_add_f32_e32 v70, v228, v70
	v_add_f32_e32 v71, v229, v71
	s_nop 0
	v_add_f32_e32 v70, v82, v70
	v_add_f32_e32 v71, v83, v71
	s_nop 0
	v_add_f32_e32 v3, v70, v71
	s_waitcnt lgkmcnt(0)
	v_mov_b32_e32 v70, v3
	s_nop 1
	v_permlane32_swap_b32_e32 v70, v3
	v_add_f32_e32 v3, v3, v70
	v_fmac_f32_e32 v3, v217, v68
.LBB0_1459:
	s_and_b64 vcc, exec, s[0:1]
	s_cbranch_vccz .LBB0_1464
	v_mov_b32_e32 v3, v157
	s_nop 0
	v_mul_f32_e64 v50, v69, -v3
	v_mov_b32_e32 v68, v3
	v_fma_f32 v36, 0, v3, v50
	v_add_f32_e32 v52, v2, v36
	v_add_f32_e32 v53, v3, v36
	v_fma_f32 v54, v68, s64, v36
	v_fma_f32 v55, v68, s65, v36
	v_fmamk_f32 v36, v3, 0x41000000, v50
	v_add_f32_e32 v56, v2, v36
	v_add_f32_e32 v57, v3, v36
	v_fma_f32 v58, v68, s64, v36
	v_fma_f32 v59, v68, s65, v36
	v_fmamk_f32 v36, v3, 0x41800000, v50
	v_add_f32_e32 v60, v2, v36
	v_add_f32_e32 v61, v3, v36
	v_fma_f32 v62, v68, s64, v36
	v_fma_f32 v63, v68, s65, v36
	v_fmamk_f32 v36, v3, 0x41c00000, v50
	v_add_f32_e32 v64, v2, v36
	v_add_f32_e32 v65, v3, v36
	v_fma_f32 v66, v68, s64, v36
	v_fma_f32 v67, v68, s65, v36
	ds_read_b128 v[36:39], v220 offset:17920
	ds_read_b128 v[40:43], v220 offset:17952
	s_waitcnt lgkmcnt(1)
	v_mfma_f32_32x32x16_bf16 v[52:67], v[36:39], v[100:103], v[52:67]
	ds_read_b128 v[36:39], v220 offset:17984
	v_fmamk_f32 v46, v3, 0x42400000, v50
	v_add_f32_e64 v44, v2, v46
	v_add_f32_e64 v45, v3, v46
	v_fma_f32 v47, v68, s65, v46
	v_fma_f32 v46, v68, s64, v46
	s_waitcnt lgkmcnt(1)
	v_mfma_f32_32x32x16_bf16 v[52:67], v[40:43], v[104:107], v[52:67]
	v_fmamk_f32 v42, v3, 0x42200000, v50
	v_add_f32_e64 v40, v2, v42
	v_add_f32_e64 v41, v3, v42
	v_fma_f32 v43, v68, s65, v42
	v_fma_f32 v42, v68, s64, v42
	s_waitcnt lgkmcnt(0)
	v_mfma_f32_32x32x16_bf16 v[52:67], v[36:39], v[108:111], v[52:67]
	ds_read_b128 v[36:39], v220 offset:18016
	s_waitcnt lgkmcnt(0)
	v_mfma_f32_32x32x16_bf16 v[52:67], v[36:39], v[112:115], v[52:67]
	v_fmamk_f32 v38, v3, 0x42000000, v50
	v_fmac_f32_e32 v50, 0x42600000, v3
	v_add_f32_e64 v36, v2, v38
	v_add_f32_e64 v37, v3, v38
	v_fma_f32 v39, v68, s65, v38
	v_fma_f32 v38, v68, s64, v38
	v_add_f32_e32 v48, v2, v50
	v_add_f32_e32 v49, v3, v50
	v_fma_f32 v51, v68, s65, v50
	v_fma_f32 v50, v68, s64, v50
	ds_read_b128 v[68:71], v219 offset:17920
	ds_read_b128 v[72:75], v219 offset:17952
	s_waitcnt lgkmcnt(1)
	v_mfma_f32_32x32x16_bf16 v[36:51], v[68:71], v[100:103], v[36:51]
	ds_read_b128 v[68:71], v219 offset:17984
	v_max3_f32 v3, v52, s97, v53
	v_max3_f32 v3, v3, v54, v55
	v_max3_f32 v3, v3, v56, v57
	v_max3_f32 v3, v3, v58, v59
	v_max3_f32 v3, v3, v60, v61
	v_max3_f32 v3, v3, v62, v63
	s_waitcnt lgkmcnt(1)
	v_mfma_f32_32x32x16_bf16 v[36:51], v[72:75], v[104:107], v[36:51]
	v_max3_f32 v3, v3, v64, v65
	v_max3_f32 v3, v3, v66, v67
	s_waitcnt lgkmcnt(0)
	v_mfma_f32_32x32x16_bf16 v[36:51], v[68:71], v[108:111], v[36:51]
	ds_read_b128 v[68:71], v219 offset:18016
	s_waitcnt lgkmcnt(0)
	v_mfma_f32_32x32x16_bf16 v[36:51], v[68:71], v[112:115], v[36:51]
	s_nop 11
	v_max3_f32 v3, v3, v36, v37
	v_max3_f32 v3, v3, v38, v39
	v_max3_f32 v3, v3, v40, v41
	v_max3_f32 v3, v3, v42, v43
	v_max3_f32 v3, v3, v44, v45
	v_max3_f32 v3, v3, v46, v47
	v_max3_f32 v3, v3, v48, v49
	v_max3_f32 v3, v3, v50, v51
	s_waitcnt lgkmcnt(0)
	v_mov_b32_e32 v68, v3
	s_nop 1
	v_permlane32_swap_b32_e32 v68, v3
	v_max_f32_e32 v68, v68, v68
	v_max_f32_e32 v3, v3, v68
	v_max3_f32 v132, v218, v3, s46
	v_sub_f32_e32 v3, v218, v132
	v_exp_f32_e32 v68, v3
	s_nop 0
	v_cmp_eq_f32_e32 vcc, 1.0, v68
	s_cmp_eq_u64 vcc, exec
	s_cbranch_scc1 .LBB0_1462
	v_mul_f32_e32 v34, v34, v68
	v_mul_f32_e32 v35, v35, v68
	v_mul_f32_e32 v32, v32, v68
	v_mul_f32_e32 v33, v33, v68
	v_mul_f32_e32 v30, v30, v68
	v_mul_f32_e32 v31, v31, v68
	v_mul_f32_e32 v28, v28, v68
	v_mul_f32_e32 v29, v29, v68
	v_mul_f32_e32 v26, v26, v68
	v_mul_f32_e32 v27, v27, v68
	v_mul_f32_e32 v24, v24, v68
	v_mul_f32_e32 v25, v25, v68
	v_mul_f32_e32 v22, v22, v68
	v_mul_f32_e32 v23, v23, v68
	v_mul_f32_e32 v20, v20, v68
	v_mul_f32_e32 v21, v21, v68
	v_mul_f32_e32 v18, v18, v68
	v_mul_f32_e32 v19, v19, v68
	v_mul_f32_e32 v16, v16, v68
	v_mul_f32_e32 v17, v17, v68
	v_mul_f32_e32 v14, v14, v68
	v_mul_f32_e32 v15, v15, v68
	v_mul_f32_e32 v12, v12, v68
	v_mul_f32_e32 v13, v13, v68
	v_mul_f32_e32 v10, v10, v68
	v_mul_f32_e32 v11, v11, v68
	v_mul_f32_e32 v8, v8, v68
	v_mul_f32_e32 v9, v9, v68
	v_mul_f32_e32 v6, v6, v68
	v_mul_f32_e32 v7, v7, v68
	v_mul_f32_e32 v4, v4, v68
	v_mul_f32_e32 v5, v5, v68
.LBB0_1462:
	v_add_u32_e32 v3, v165, v196
	v_sub_f32_e32 v52, v52, v132
	v_sub_f32_e32 v53, v53, v132
	v_sub_f32_e32 v54, v54, v132
	v_sub_f32_e32 v55, v55, v132
	v_sub_f32_e32 v56, v56, v132
	v_sub_f32_e32 v57, v57, v132
	v_sub_f32_e32 v58, v58, v132
	v_sub_f32_e32 v59, v59, v132
	v_add_u32_e32 v69, v3, v190
	v_exp_f32_e32 v52, v52
	v_exp_f32_e32 v53, v53
	v_exp_f32_e32 v54, v54
	v_exp_f32_e32 v55, v55
	v_exp_f32_e32 v56, v56
	v_exp_f32_e32 v57, v57
	v_exp_f32_e32 v58, v58
	v_exp_f32_e32 v59, v59
	v_add_u32_e32 v69, 0x6800, v69
	ds_read2_b64 v[74:77], v69 offset0:64 offset1:66
	ds_read2_b64 v[78:81], v69 offset0:68 offset1:70
	v_add_u32_e32 v3, v3, v191
	v_cvt_pk_bf16_f32 v70, v52, v53
	v_cvt_pk_bf16_f32 v71, v54, v55
	v_cvt_pk_bf16_f32 v72, v56, v57
	v_cvt_pk_bf16_f32 v73, v58, v59
	v_add_u32_e32 v3, 0x6800, v3
	v_sub_f32_e32 v60, v60, v132
	v_sub_f32_e32 v61, v61, v132
	s_waitcnt lgkmcnt(1)
	v_mfma_f32_32x32x16_bf16 v[20:35], v[74:77], v[70:73], v[20:35]
	ds_read2_b64 v[74:77], v3 offset0:64 offset1:66
	ds_read2_b64 v[82:85], v3 offset0:68 offset1:70
	v_add_f32_e64 v62, v62, -v132
	v_add_f32_e64 v63, v63, -v132
	v_add_f32_e64 v64, v64, -v132
	v_add_f32_e64 v65, v65, -v132
	v_sub_f32_e32 v66, v66, v132
	v_sub_f32_e32 v67, v67, v132
	v_exp_f32_e32 v60, v60
	v_exp_f32_e32 v61, v61
	v_exp_f32_e32 v62, v62
	s_waitcnt lgkmcnt(1)
	v_mfma_f32_32x32x16_bf16 v[4:19], v[74:77], v[70:73], v[4:19]
	v_exp_f32_e32 v63, v63
	v_exp_f32_e32 v64, v64
	v_exp_f32_e32 v65, v65
	v_exp_f32_e32 v66, v66
	v_exp_f32_e32 v67, v67
	v_cvt_pk_bf16_f32 v70, v60, v61
	v_cvt_pk_bf16_f32 v71, v62, v63
	v_cvt_pk_bf16_f32 v72, v64, v65
	v_cvt_pk_bf16_f32 v73, v66, v67
	s_nop 1
	v_mfma_f32_32x32x16_bf16 v[20:35], v[78:81], v[70:73], v[20:35]
	s_waitcnt lgkmcnt(0)
	v_mfma_f32_32x32x16_bf16 v[4:19], v[82:85], v[70:73], v[4:19]
	v_add_f32_e64 v42, v42, -v132
	v_add_f32_e64 v43, v43, -v132
	v_add_f32_e64 v36, v36, -v132
	v_add_f32_e64 v37, v37, -v132
	v_add_f32_e64 v38, v38, -v132
	v_add_f32_e64 v39, v39, -v132
	v_sub_f32_e32 v40, v40, v132
	v_sub_f32_e32 v41, v41, v132
	v_exp_f32_e32 v78, v42
	v_exp_f32_e32 v79, v43
	v_sub_f32_e32 v42, v44, v132
	v_sub_f32_e32 v43, v45, v132
	v_exp_f32_e32 v36, v36
	v_exp_f32_e32 v37, v37
	v_exp_f32_e32 v38, v38
	v_exp_f32_e32 v39, v39
	v_exp_f32_e32 v40, v40
	v_exp_f32_e32 v41, v41
	v_exp_f32_e32 v80, v42
	v_exp_f32_e32 v81, v43
	v_sub_f32_e32 v42, v46, v132
	v_sub_f32_e32 v43, v47, v132
	v_cvt_pk_bf16_f32 v44, v40, v41
	v_exp_f32_e32 v82, v42
	v_exp_f32_e32 v83, v43
	v_sub_f32_e32 v42, v48, v132
	v_sub_f32_e32 v43, v49, v132
	ds_read2_b64 v[46:49], v69 offset0:72 offset1:74
	ds_read2_b64 v[70:73], v69 offset0:76 offset1:78
	v_exp_f32_e32 v84, v42
	v_exp_f32_e32 v85, v43
	v_sub_f32_e32 v42, v50, v132
	v_sub_f32_e32 v43, v51, v132
	v_cvt_pk_bf16_f32 v45, v78, v79
	v_exp_f32_e32 v50, v42
	v_exp_f32_e32 v51, v43
	v_cvt_pk_bf16_f32 v42, v36, v37
	v_cvt_pk_bf16_f32 v43, v38, v39
	s_waitcnt lgkmcnt(1)
	s_nop 0
	v_mfma_f32_32x32x16_bf16 v[20:35], v[46:49], v[42:45], v[20:35]
	ds_read2_b64 v[46:49], v3 offset0:72 offset1:74
	ds_read2_b64 v[74:77], v3 offset0:76 offset1:78
	s_waitcnt lgkmcnt(1)
	v_mfma_f32_32x32x16_bf16 v[4:19], v[46:49], v[42:45], v[4:19]
	v_cvt_pk_bf16_f32 v42, v80, v81
	v_cvt_pk_bf16_f32 v43, v82, v83
	v_cvt_pk_bf16_f32 v44, v84, v85
	v_cvt_pk_bf16_f32 v45, v50, v51
	s_nop 1
	v_mfma_f32_32x32x16_bf16 v[20:35], v[70:73], v[42:45], v[20:35]
	s_waitcnt lgkmcnt(0)
	v_mfma_f32_32x32x16_bf16 v[4:19], v[74:77], v[42:45], v[4:19]
	v_add_f32_e64 v42, v52, 0
	v_add_f32_e64 v43, v53, 0
	v_add_f32_e64 v42, v54, v42
	v_add_f32_e64 v43, v55, v43
	v_add_f32_e64 v42, v56, v42
	v_add_f32_e64 v43, v57, v43
	v_add_f32_e32 v42, v58, v42
	v_add_f32_e32 v43, v59, v43
	s_nop 0
	v_add_f32_e32 v42, v60, v42
	v_add_f32_e32 v43, v61, v43
	s_nop 0
	v_add_f32_e32 v42, v62, v42
	v_add_f32_e32 v43, v63, v43
	s_nop 0
	v_add_f32_e32 v42, v64, v42
	v_add_f32_e32 v43, v65, v43
	s_nop 0
	v_add_f32_e32 v42, v66, v42
	v_add_f32_e32 v43, v67, v43
	s_nop 0
	v_add_f32_e32 v36, v36, v42
	v_add_f32_e32 v37, v37, v43
	s_nop 0
	v_add_f32_e32 v36, v38, v36
	v_add_f32_e32 v37, v39, v37
	s_nop 0
	v_add_f32_e32 v36, v40, v36
	v_add_f32_e32 v37, v41, v37
	s_nop 0
	v_add_f32_e32 v36, v78, v36
	v_add_f32_e32 v37, v79, v37
	s_nop 0
	v_add_f32_e32 v36, v80, v36
	v_add_f32_e32 v37, v81, v37
	s_nop 0
	v_add_f32_e32 v36, v82, v36
	v_add_f32_e32 v37, v83, v37
	s_nop 0
	v_add_f32_e32 v36, v84, v36
	v_add_f32_e32 v37, v85, v37
	s_nop 0
	v_add_f32_e32 v36, v50, v36
	v_add_f32_e32 v37, v51, v37
	s_nop 0
	v_add_f32_e32 v3, v36, v37
	s_waitcnt lgkmcnt(0)
	v_mov_b32_e32 v36, v3
	s_nop 1
	v_permlane32_swap_b32_e32 v36, v3
	v_add_f32_e32 v3, v3, v36
	s_nop 0
	v_fmac_f32_e32 v3, v217, v68
	s_nop 6
	s_branch .LBB0_1464
